# select: wave count reductions via DPP row scan instead of 6-step ds_bpermute butterfly
# speedup vs baseline: 1.0039x; 1.0039x over previous
; template <int NJ>
; DI void select_row(const float* row, int n, u64* bmrow, int lane) {
;     ...
;     unsigned cand = km & 0xff800000u;
; #pragma unroll 1
;     for (int pr = 0; pr < 4; ++pr) {
;       if (cand <= lo || cand >= hi) break;
;       int c = 0;
; #pragma unroll
;       for (int jj = 0; jj < NJ; ++jj)
;         asm volatile("v_cmp_le_u32 vcc, %1, %2\n\tv_addc_co_u32 %0, vcc, 0, %0, vcc" : "+v"(c) : "s"(cand), "v"(key[jj]) : "vcc");
;       c = wave_sum_i(c, lane);
;       if (c == 256) { T = cand; exact = true; break; }
;       if (c > 256) { lo = cand; break; }
;       hi = cand;
;       if (cand < 0x00800000u) break;
;       cand -= 0x00800000u;
;     }
.LBB0_638:
	v_cmp_gt_u32_e32 vcc, v231, v230
	v_cmp_lt_u32_e64 s[6:7], v231, v34
	s_and_b64 s[40:41], vcc, s[6:7]
	s_andn2_b64 s[6:7], s[26:27], exec
	s_and_b64 s[26:27], s[38:39], exec
	s_or_b64 s[26:27], s[6:7], s[26:27]
	s_or_b64 s[24:25], s[24:25], exec
	s_and_saveexec_b64 s[6:7], s[40:41]
	s_cbranch_execz .LBB0_637
	v_mov_b32_e32 v38, v1
	v_cmp_le_u32 vcc, v231, v79
	v_addc_co_u32 v38, vcc, 0, v38, vcc
	s_movk_i32 s40, 0x100
	v_cmp_le_u32 vcc, v231, v77
	v_addc_co_u32 v38, vcc, 0, v38, vcc
	s_mov_b64 s[44:45], -1
	v_cmp_le_u32 vcc, v231, v75
	v_addc_co_u32 v38, vcc, 0, v38, vcc
	s_mov_b64 s[42:43], -1
	v_cmp_le_u32 vcc, v231, v73
	v_addc_co_u32 v38, vcc, 0, v38, vcc
	s_nop 0
	v_cmp_le_u32 vcc, v231, v71
	v_addc_co_u32 v38, vcc, 0, v38, vcc
	s_nop 0
	v_cmp_le_u32 vcc, v231, v69
	v_addc_co_u32 v38, vcc, 0, v38, vcc
	s_nop 0
	v_cmp_le_u32 vcc, v231, v67
	v_addc_co_u32 v38, vcc, 0, v38, vcc
	s_nop 0
	v_cmp_le_u32 vcc, v231, v65
	v_addc_co_u32 v38, vcc, 0, v38, vcc
	s_nop 0
	v_cmp_le_u32 vcc, v231, v63
	v_addc_co_u32 v38, vcc, 0, v38, vcc
	s_nop 0
	v_cmp_le_u32 vcc, v231, v61
	v_addc_co_u32 v38, vcc, 0, v38, vcc
	s_nop 0
	v_cmp_le_u32 vcc, v231, v59
	v_addc_co_u32 v38, vcc, 0, v38, vcc
	s_nop 0
	v_cmp_le_u32 vcc, v231, v57
	v_addc_co_u32 v38, vcc, 0, v38, vcc
	s_nop 0
	v_cmp_le_u32 vcc, v231, v55
	v_addc_co_u32 v38, vcc, 0, v38, vcc
	s_nop 0
	v_cmp_le_u32 vcc, v231, v51
	v_addc_co_u32 v38, vcc, 0, v38, vcc
	s_nop 0
	v_cmp_le_u32 vcc, v231, v53
	v_addc_co_u32 v38, vcc, 0, v38, vcc
	s_nop 0
	v_cmp_le_u32 vcc, v231, v49
	v_addc_co_u32 v38, vcc, 0, v38, vcc
	s_nop 0
	v_cmp_le_u32 vcc, v231, v47
	v_addc_co_u32 v38, vcc, 0, v38, vcc
	s_nop 0
	v_cmp_le_u32 vcc, v231, v45
	v_addc_co_u32 v38, vcc, 0, v38, vcc
	s_nop 0
	v_cmp_le_u32 vcc, v231, v43
	v_addc_co_u32 v38, vcc, 0, v38, vcc
	s_nop 0
	v_cmp_le_u32 vcc, v231, v41
	v_addc_co_u32 v38, vcc, 0, v38, vcc
	s_nop 0
	v_cmp_le_u32 vcc, v231, v39
	v_addc_co_u32 v38, vcc, 0, v38, vcc
	s_nop 0
	v_cmp_le_u32 vcc, v231, v37
	v_addc_co_u32 v38, vcc, 0, v38, vcc
	s_nop 0
	v_cmp_le_u32 vcc, v231, v35
	v_addc_co_u32 v38, vcc, 0, v38, vcc
	s_nop 0
	v_cmp_le_u32 vcc, v231, v33
	v_addc_co_u32 v38, vcc, 0, v38, vcc
	s_nop 0
	v_cmp_le_u32 vcc, v231, v31
	v_addc_co_u32 v38, vcc, 0, v38, vcc
	s_nop 0
	v_cmp_le_u32 vcc, v231, v29
	v_addc_co_u32 v38, vcc, 0, v38, vcc
	s_nop 0
	v_cmp_le_u32 vcc, v231, v27
	v_addc_co_u32 v38, vcc, 0, v38, vcc
	s_nop 0
	v_cmp_le_u32 vcc, v231, v25
	v_addc_co_u32 v38, vcc, 0, v38, vcc
	s_nop 0
	v_cmp_le_u32 vcc, v231, v23
	v_addc_co_u32 v38, vcc, 0, v38, vcc
	s_nop 0
	v_cmp_le_u32 vcc, v231, v21
	v_addc_co_u32 v38, vcc, 0, v38, vcc
	s_nop 0
	v_cmp_le_u32 vcc, v231, v19
	v_addc_co_u32 v38, vcc, 0, v38, vcc
	s_nop 0
	v_cmp_le_u32 vcc, v231, v17
	v_addc_co_u32 v38, vcc, 0, v38, vcc
	s_nop 0
	v_cmp_le_u32 vcc, v231, v30
	v_addc_co_u32 v38, vcc, 0, v38, vcc
	s_nop 0
	v_cmp_le_u32 vcc, v231, v28
	v_addc_co_u32 v38, vcc, 0, v38, vcc
	s_nop 0
	v_cmp_le_u32 vcc, v231, v26
	v_addc_co_u32 v38, vcc, 0, v38, vcc
	s_nop 0
	v_cmp_le_u32 vcc, v231, v24
	v_addc_co_u32 v38, vcc, 0, v38, vcc
	s_nop 0
	v_cmp_le_u32 vcc, v231, v22
	v_addc_co_u32 v38, vcc, 0, v38, vcc
	s_nop 0
	v_cmp_le_u32 vcc, v231, v20
	v_addc_co_u32 v38, vcc, 0, v38, vcc
	s_nop 0
	v_cmp_le_u32 vcc, v231, v18
	v_addc_co_u32 v38, vcc, 0, v38, vcc
	s_nop 0
	v_cmp_le_u32 vcc, v231, v16
	v_addc_co_u32 v38, vcc, 0, v38, vcc
	s_nop 0
	v_cmp_le_u32 vcc, v231, v14
	v_addc_co_u32 v38, vcc, 0, v38, vcc
	s_nop 0
	v_cmp_le_u32 vcc, v231, v12
	v_addc_co_u32 v38, vcc, 0, v38, vcc
	s_nop 0
	v_cmp_le_u32 vcc, v231, v10
	v_addc_co_u32 v38, vcc, 0, v38, vcc
	s_nop 0
	v_cmp_le_u32 vcc, v231, v8
	v_addc_co_u32 v38, vcc, 0, v38, vcc
	s_nop 0
	v_cmp_le_u32 vcc, v231, v6
	v_addc_co_u32 v38, vcc, 0, v38, vcc
	s_nop 0
	v_cmp_le_u32 vcc, v231, v4
	v_addc_co_u32 v38, vcc, 0, v38, vcc
	s_nop 0
	v_cmp_le_u32 vcc, v231, v240
	v_addc_co_u32 v38, vcc, 0, v38, vcc
	s_nop 0
	v_cmp_le_u32 vcc, v231, v236
	v_addc_co_u32 v38, vcc, 0, v38, vcc
	s_nop 0
	v_cmp_le_u32 vcc, v231, v211
	v_addc_co_u32 v38, vcc, 0, v38, vcc
	s_nop 0
	v_cmp_le_u32 vcc, v231, v239
	v_addc_co_u32 v38, vcc, 0, v38, vcc
	s_nop 0
	v_cmp_le_u32 vcc, v231, v227
	v_addc_co_u32 v38, vcc, 0, v38, vcc
	s_nop 0
	v_cmp_le_u32 vcc, v231, v253
	v_addc_co_u32 v38, vcc, 0, v38, vcc
	s_nop 0
	v_cmp_le_u32 vcc, v231, v252
	v_addc_co_u32 v38, vcc, 0, v38, vcc
	s_nop 0
	v_cmp_le_u32 vcc, v231, v251
	v_addc_co_u32 v38, vcc, 0, v38, vcc
	s_nop 0
	v_cmp_le_u32 vcc, v231, v250
	v_addc_co_u32 v38, vcc, 0, v38, vcc
	s_nop 0
	v_cmp_le_u32 vcc, v231, v249
	v_addc_co_u32 v38, vcc, 0, v38, vcc
	s_nop 0
	v_cmp_le_u32 vcc, v231, v248
	v_addc_co_u32 v38, vcc, 0, v38, vcc
	s_nop 0
	v_cmp_le_u32 vcc, v231, v247
	v_addc_co_u32 v38, vcc, 0, v38, vcc
	s_nop 0
	v_cmp_le_u32 vcc, v231, v246
	v_addc_co_u32 v38, vcc, 0, v38, vcc
	s_nop 0
	v_cmp_le_u32 vcc, v231, v245
	v_addc_co_u32 v38, vcc, 0, v38, vcc
	s_nop 0
	v_cmp_le_u32 vcc, v231, v244
	v_addc_co_u32 v38, vcc, 0, v38, vcc
	s_nop 0
	v_cmp_le_u32 vcc, v231, v233
	v_addc_co_u32 v38, vcc, 0, v38, vcc
	s_nop 0
	v_cmp_le_u32 vcc, v231, v232
	v_addc_co_u32 v38, vcc, 0, v38, vcc
	s_nop 0
	v_cmp_le_u32 vcc, v231, v0
	v_addc_co_u32 v38, vcc, 0, v38, vcc
	s_nop 0
	v_cmp_le_u32 vcc, v231, v83
	v_addc_co_u32 v38, vcc, 0, v38, vcc
	s_nop 0
	v_cmp_le_u32 vcc, v231, v81
	v_addc_co_u32 v38, vcc, 0, v38, vcc
	s_nop 0
	v_cmp_le_u32 vcc, v231, v87
	v_addc_co_u32 v38, vcc, 0, v38, vcc
	s_nop 0
	v_cmp_le_u32 vcc, v231, v85
	v_addc_co_u32 v38, vcc, 0, v38, vcc
	s_nop 0
	v_cmp_le_u32 vcc, v231, v91
	v_addc_co_u32 v38, vcc, 0, v38, vcc
; DI int shflxi(int v, int m, int lane) { return __builtin_amdgcn_ds_bpermute((lane ^ m) << 2, v); }
; DI int wave_sum_i(int v, int lane) {
; #pragma unroll
;   for (int o = 32; o > 0; o >>= 1) v += shflxi(v, o, lane);
;   return v;
; }
; template <int NJ>
; DI void select_row(const float* row, int n, u64* bmrow, int lane) {
;     ...
;     unsigned cand = km & 0xff800000u;
; #pragma unroll 1
;     for (int pr = 0; pr < 4; ++pr) {
;       if (cand <= lo || cand >= hi) break;
;       int c = 0;
; #pragma unroll
;       for (int jj = 0; jj < NJ; ++jj)
;         asm volatile("v_cmp_le_u32 vcc, %1, %2\n\tv_addc_co_u32 %0, vcc, 0, %0, vcc" : "+v"(c) : "s"(cand), "v"(key[jj]) : "vcc");
;       c = wave_sum_i(c, lane);
;       if (c == 256) { T = cand; exact = true; break; }
;       if (c > 256) { lo = cand; break; }
;       hi = cand;
;       if (cand < 0x00800000u) break;
;       cand -= 0x00800000u;
;     }
	s_nop 0
	v_cmp_le_u32 vcc, v231, v89
	v_addc_co_u32 v38, vcc, 0, v38, vcc
	s_nop 0
	v_cmp_le_u32 vcc, v231, v95
	v_addc_co_u32 v38, vcc, 0, v38, vcc
	s_nop 0
	v_cmp_le_u32 vcc, v231, v93
	v_addc_co_u32 v38, vcc, 0, v38, vcc
	s_nop 0
	v_cmp_le_u32 vcc, v231, v99
	v_addc_co_u32 v38, vcc, 0, v38, vcc
	s_nop 0
	v_cmp_le_u32 vcc, v231, v97
	v_addc_co_u32 v38, vcc, 0, v38, vcc
	s_nop 0
	v_cmp_le_u32 vcc, v231, v103
	v_addc_co_u32 v38, vcc, 0, v38, vcc
	s_nop 0
	v_cmp_le_u32 vcc, v231, v101
	v_addc_co_u32 v38, vcc, 0, v38, vcc
	s_nop 0
	v_cmp_le_u32 vcc, v231, v107
	v_addc_co_u32 v38, vcc, 0, v38, vcc
	s_nop 0
	v_cmp_le_u32 vcc, v231, v105
	v_addc_co_u32 v38, vcc, 0, v38, vcc
	s_nop 0
	v_cmp_le_u32 vcc, v231, v111
	v_addc_co_u32 v38, vcc, 0, v38, vcc
	s_nop 0
	v_cmp_le_u32 vcc, v231, v109
	v_addc_co_u32 v38, vcc, 0, v38, vcc
	s_nop 0
	v_cmp_le_u32 vcc, v231, v115
	v_addc_co_u32 v38, vcc, 0, v38, vcc
	s_nop 0
	v_cmp_le_u32 vcc, v231, v113
	v_addc_co_u32 v38, vcc, 0, v38, vcc
	s_nop 0
	v_cmp_le_u32 vcc, v231, v119
	v_addc_co_u32 v38, vcc, 0, v38, vcc
	s_nop 0
	v_cmp_le_u32 vcc, v231, v117
	v_addc_co_u32 v38, vcc, 0, v38, vcc
	s_nop 0
	v_cmp_le_u32 vcc, v231, v123
	v_addc_co_u32 v38, vcc, 0, v38, vcc
	s_nop 0
	v_cmp_le_u32 vcc, v231, v121
	v_addc_co_u32 v38, vcc, 0, v38, vcc
	s_nop 0
	v_cmp_le_u32 vcc, v231, v127
	v_addc_co_u32 v38, vcc, 0, v38, vcc
	s_nop 0
	v_cmp_le_u32 vcc, v231, v125
	v_addc_co_u32 v38, vcc, 0, v38, vcc
	s_nop 0
	v_cmp_le_u32 vcc, v231, v131
	v_addc_co_u32 v38, vcc, 0, v38, vcc
	s_nop 0
	v_cmp_le_u32 vcc, v231, v129
	v_addc_co_u32 v38, vcc, 0, v38, vcc
	s_nop 0
	v_cmp_le_u32 vcc, v231, v135
	v_addc_co_u32 v38, vcc, 0, v38, vcc
	s_nop 0
	v_cmp_le_u32 vcc, v231, v133
	v_addc_co_u32 v38, vcc, 0, v38, vcc
	s_nop 0
	v_cmp_le_u32 vcc, v231, v139
	v_addc_co_u32 v38, vcc, 0, v38, vcc
	s_nop 0
	v_cmp_le_u32 vcc, v231, v137
	v_addc_co_u32 v38, vcc, 0, v38, vcc
	s_nop 0
	v_cmp_le_u32 vcc, v231, v143
	v_addc_co_u32 v38, vcc, 0, v38, vcc
	s_nop 0
	v_cmp_le_u32 vcc, v231, v141
	v_addc_co_u32 v38, vcc, 0, v38, vcc
	s_nop 0
	v_cmp_le_u32 vcc, v231, v147
	v_addc_co_u32 v38, vcc, 0, v38, vcc
	s_nop 0
	v_cmp_le_u32 vcc, v231, v145
	v_addc_co_u32 v38, vcc, 0, v38, vcc
	s_nop 0
	v_cmp_le_u32 vcc, v231, v151
	v_addc_co_u32 v38, vcc, 0, v38, vcc
	s_nop 0
	v_cmp_le_u32 vcc, v231, v149
	v_addc_co_u32 v38, vcc, 0, v38, vcc
	s_nop 0
	v_cmp_le_u32 vcc, v231, v155
	v_addc_co_u32 v38, vcc, 0, v38, vcc
	s_nop 0
	v_cmp_le_u32 vcc, v231, v153
	v_addc_co_u32 v38, vcc, 0, v38, vcc
	s_nop 0
	v_cmp_le_u32 vcc, v231, v159
	v_addc_co_u32 v38, vcc, 0, v38, vcc
	s_nop 0
	v_cmp_le_u32 vcc, v231, v157
	v_addc_co_u32 v38, vcc, 0, v38, vcc
	s_nop 0
	v_cmp_le_u32 vcc, v231, v163
	v_addc_co_u32 v38, vcc, 0, v38, vcc
	s_nop 0
	v_cmp_le_u32 vcc, v231, v161
	v_addc_co_u32 v38, vcc, 0, v38, vcc
	s_nop 0
	v_cmp_le_u32 vcc, v231, v167
	v_addc_co_u32 v38, vcc, 0, v38, vcc
	s_nop 0
	v_cmp_le_u32 vcc, v231, v165
	v_addc_co_u32 v38, vcc, 0, v38, vcc
	s_nop 0
	v_cmp_le_u32 vcc, v231, v171
	v_addc_co_u32 v38, vcc, 0, v38, vcc
	s_nop 0
	v_cmp_le_u32 vcc, v231, v169
	v_addc_co_u32 v38, vcc, 0, v38, vcc
	s_nop 0
	v_cmp_le_u32 vcc, v231, v175
	v_addc_co_u32 v38, vcc, 0, v38, vcc
	s_nop 0
	v_cmp_le_u32 vcc, v231, v173
	v_addc_co_u32 v38, vcc, 0, v38, vcc
	s_nop 0
	v_cmp_le_u32 vcc, v231, v179
	v_addc_co_u32 v38, vcc, 0, v38, vcc
	s_nop 0
	v_cmp_le_u32 vcc, v231, v177
	v_addc_co_u32 v38, vcc, 0, v38, vcc
	s_nop 0
	v_cmp_le_u32 vcc, v231, v183
	v_addc_co_u32 v38, vcc, 0, v38, vcc
	s_nop 0
	v_cmp_le_u32 vcc, v231, v181
	v_addc_co_u32 v38, vcc, 0, v38, vcc
	s_nop 0
	v_cmp_le_u32 vcc, v231, v187
	v_addc_co_u32 v38, vcc, 0, v38, vcc
	s_nop 0
	v_cmp_le_u32 vcc, v231, v185
	v_addc_co_u32 v38, vcc, 0, v38, vcc
	s_nop 0
	v_cmp_le_u32 vcc, v231, v191
	v_addc_co_u32 v38, vcc, 0, v38, vcc
	s_nop 0
	v_cmp_le_u32 vcc, v231, v189
	v_addc_co_u32 v38, vcc, 0, v38, vcc
	s_nop 0
	v_cmp_le_u32 vcc, v231, v195
	v_addc_co_u32 v38, vcc, 0, v38, vcc
	s_nop 0
	v_cmp_le_u32 vcc, v231, v193
	v_addc_co_u32 v38, vcc, 0, v38, vcc
	s_nop 0
	v_cmp_le_u32 vcc, v231, v199
	v_addc_co_u32 v38, vcc, 0, v38, vcc
	s_nop 0
	v_cmp_le_u32 vcc, v231, v197
	v_addc_co_u32 v38, vcc, 0, v38, vcc
	s_nop 0
	v_cmp_le_u32 vcc, v231, v235
	v_addc_co_u32 v38, vcc, 0, v38, vcc
	s_nop 0
	v_cmp_le_u32 vcc, v231, v234
	v_addc_co_u32 v38, vcc, 0, v38, vcc
	s_nop 0
	v_cmp_le_u32 vcc, v231, v243
	v_addc_co_u32 v38, vcc, 0, v38, vcc
	s_nop 0
	v_cmp_le_u32 vcc, v231, v242
	v_addc_co_u32 v38, vcc, 0, v38, vcc
	s_nop 1
	v_add_u32_dpp v38, v38, v38 row_shr:1 row_mask:0xf bank_mask:0xf bound_ctrl:0
	s_nop 1
	v_add_u32_dpp v38, v38, v38 row_shr:2 row_mask:0xf bank_mask:0xf bound_ctrl:0
	s_nop 1
	v_add_u32_dpp v38, v38, v38 row_shr:4 row_mask:0xf bank_mask:0xf bound_ctrl:0
	s_nop 1
	v_add_u32_dpp v38, v38, v38 row_shr:8 row_mask:0xf bank_mask:0xf bound_ctrl:0
	s_nop 1
	v_add_u32_dpp v38, v38, v38 row_bcast:15 row_mask:0xa bank_mask:0xf
	s_nop 1
	v_add_u32_dpp v38, v38, v38 row_bcast:31 row_mask:0xc bank_mask:0xf
	s_nop 1
	v_readlane_b32 s98, v38, 63
	s_nop 1
	v_mov_b32_e32 v40, s98
	v_mov_b32_e32 v38, s98
	v_cmp_ne_u32_e32 vcc, s40, v40
	v_mov_b32_e32 v38, v231
	s_and_saveexec_b64 s[40:41], vcc
	s_cbranch_execz .LBB0_636
	s_movk_i32 s42, 0x101
	v_cmp_gt_i32_e32 vcc, s42, v40
	v_mov_b32_e32 v38, v231
	s_and_saveexec_b64 s[42:43], vcc
	s_cbranch_execz .LBB0_635
	v_subrev_co_u32_e32 v34, vcc, 0x800000, v231
	s_orn2_b64 s[44:45], vcc, exec
	s_nop 0
	v_cndmask_b32_e32 v38, v34, v231, vcc
	v_mov_b32_e32 v34, v231
	v_mov_b32_e32 v231, v230
	s_branch .LBB0_635

; template <int NJ>
; DI void select_row(const float* row, int n, u64* bmrow, int lane) {
;     ...
;   while (!exact && hi - lo > 1u) {
;     const unsigned cand = lo + ((hi - lo) >> 1);
;     int c = 0;
; #pragma unroll
;     for (int jj = 0; jj < NJ; ++jj)
;       asm volatile("v_cmp_le_u32 vcc, %1, %2\n\tv_addc_co_u32 %0, vcc, 0, %0, vcc" : "+v"(c) : "s"(cand), "v"(key[jj]) : "vcc");
;     c = wave_sum_i(c, lane);
;     if (c == 256) { T = cand; exact = true; }
;     else if (c > 256) lo = cand; else hi = cand;
;   }
.LBB0_644:
	v_lshrrev_b32_e32 v36, 1, v36
	v_mov_b32_e32 v38, v1
	v_add_u32_e32 v36, v230, v36
	v_cmp_le_u32 vcc, v36, v79
	v_addc_co_u32 v38, vcc, 0, v38, vcc
	s_nop 0
	v_cmp_le_u32 vcc, v36, v77
	v_addc_co_u32 v38, vcc, 0, v38, vcc
	s_nop 0
	v_cmp_le_u32 vcc, v36, v75
	v_addc_co_u32 v38, vcc, 0, v38, vcc
	s_nop 0
	v_cmp_le_u32 vcc, v36, v73
	v_addc_co_u32 v38, vcc, 0, v38, vcc
	s_nop 0
	v_cmp_le_u32 vcc, v36, v71
	v_addc_co_u32 v38, vcc, 0, v38, vcc
	s_nop 0
	v_cmp_le_u32 vcc, v36, v69
	v_addc_co_u32 v38, vcc, 0, v38, vcc
	s_nop 0
	v_cmp_le_u32 vcc, v36, v67
	v_addc_co_u32 v38, vcc, 0, v38, vcc
	s_nop 0
	v_cmp_le_u32 vcc, v36, v65
	v_addc_co_u32 v38, vcc, 0, v38, vcc
	s_nop 0
	v_cmp_le_u32 vcc, v36, v63
	v_addc_co_u32 v38, vcc, 0, v38, vcc
	s_nop 0
	v_cmp_le_u32 vcc, v36, v61
	v_addc_co_u32 v38, vcc, 0, v38, vcc
	s_nop 0
	v_cmp_le_u32 vcc, v36, v59
	v_addc_co_u32 v38, vcc, 0, v38, vcc
	s_nop 0
	v_cmp_le_u32 vcc, v36, v57
	v_addc_co_u32 v38, vcc, 0, v38, vcc
	s_nop 0
	v_cmp_le_u32 vcc, v36, v55
	v_addc_co_u32 v38, vcc, 0, v38, vcc
	s_nop 0
	v_cmp_le_u32 vcc, v36, v51
	v_addc_co_u32 v38, vcc, 0, v38, vcc
	s_nop 0
	v_cmp_le_u32 vcc, v36, v53
	v_addc_co_u32 v38, vcc, 0, v38, vcc
	s_nop 0
	v_cmp_le_u32 vcc, v36, v49
	v_addc_co_u32 v38, vcc, 0, v38, vcc
	s_nop 0
	v_cmp_le_u32 vcc, v36, v47
	v_addc_co_u32 v38, vcc, 0, v38, vcc
	s_nop 0
	v_cmp_le_u32 vcc, v36, v45
	v_addc_co_u32 v38, vcc, 0, v38, vcc
	s_nop 0
	v_cmp_le_u32 vcc, v36, v43
	v_addc_co_u32 v38, vcc, 0, v38, vcc
	s_nop 0
	v_cmp_le_u32 vcc, v36, v41
	v_addc_co_u32 v38, vcc, 0, v38, vcc
	s_nop 0
	v_cmp_le_u32 vcc, v36, v39
	v_addc_co_u32 v38, vcc, 0, v38, vcc
	s_nop 0
	v_cmp_le_u32 vcc, v36, v37
	v_addc_co_u32 v38, vcc, 0, v38, vcc
	s_nop 0
	v_cmp_le_u32 vcc, v36, v35
	v_addc_co_u32 v38, vcc, 0, v38, vcc
	s_nop 0
	v_cmp_le_u32 vcc, v36, v33
	v_addc_co_u32 v38, vcc, 0, v38, vcc
	s_nop 0
	v_cmp_le_u32 vcc, v36, v31
	v_addc_co_u32 v38, vcc, 0, v38, vcc
	s_nop 0
	v_cmp_le_u32 vcc, v36, v29
	v_addc_co_u32 v38, vcc, 0, v38, vcc
	s_nop 0
	v_cmp_le_u32 vcc, v36, v27
	v_addc_co_u32 v38, vcc, 0, v38, vcc
	s_nop 0
	v_cmp_le_u32 vcc, v36, v25
	v_addc_co_u32 v38, vcc, 0, v38, vcc
	s_nop 0
	v_cmp_le_u32 vcc, v36, v23
	v_addc_co_u32 v38, vcc, 0, v38, vcc
	s_nop 0
	v_cmp_le_u32 vcc, v36, v21
	v_addc_co_u32 v38, vcc, 0, v38, vcc
	s_nop 0
	v_cmp_le_u32 vcc, v36, v19
	v_addc_co_u32 v38, vcc, 0, v38, vcc
	s_nop 0
	v_cmp_le_u32 vcc, v36, v17
	v_addc_co_u32 v38, vcc, 0, v38, vcc
	s_nop 0
	v_cmp_le_u32 vcc, v36, v30
	v_addc_co_u32 v38, vcc, 0, v38, vcc
	s_nop 0
	v_cmp_le_u32 vcc, v36, v28
	v_addc_co_u32 v38, vcc, 0, v38, vcc
	s_nop 0
	v_cmp_le_u32 vcc, v36, v26
	v_addc_co_u32 v38, vcc, 0, v38, vcc
	s_nop 0
	v_cmp_le_u32 vcc, v36, v24
	v_addc_co_u32 v38, vcc, 0, v38, vcc
	s_nop 0
	v_cmp_le_u32 vcc, v36, v22
	v_addc_co_u32 v38, vcc, 0, v38, vcc
	s_nop 0
	v_cmp_le_u32 vcc, v36, v20
	v_addc_co_u32 v38, vcc, 0, v38, vcc
	s_nop 0
	v_cmp_le_u32 vcc, v36, v18
	v_addc_co_u32 v38, vcc, 0, v38, vcc
	s_nop 0
	v_cmp_le_u32 vcc, v36, v16
	v_addc_co_u32 v38, vcc, 0, v38, vcc
	s_nop 0
	v_cmp_le_u32 vcc, v36, v14
	v_addc_co_u32 v38, vcc, 0, v38, vcc
	s_nop 0
	v_cmp_le_u32 vcc, v36, v12
	v_addc_co_u32 v38, vcc, 0, v38, vcc
	s_nop 0
	v_cmp_le_u32 vcc, v36, v10
	v_addc_co_u32 v38, vcc, 0, v38, vcc
	s_nop 0
	v_cmp_le_u32 vcc, v36, v8
	v_addc_co_u32 v38, vcc, 0, v38, vcc
	s_nop 0
	v_cmp_le_u32 vcc, v36, v6
	v_addc_co_u32 v38, vcc, 0, v38, vcc
	s_nop 0
	v_cmp_le_u32 vcc, v36, v4
	v_addc_co_u32 v38, vcc, 0, v38, vcc
	s_nop 0
	v_cmp_le_u32 vcc, v36, v240
	v_addc_co_u32 v38, vcc, 0, v38, vcc
	s_nop 0
	v_cmp_le_u32 vcc, v36, v236
	v_addc_co_u32 v38, vcc, 0, v38, vcc
	s_nop 0
	v_cmp_le_u32 vcc, v36, v211
	v_addc_co_u32 v38, vcc, 0, v38, vcc
	s_nop 0
	v_cmp_le_u32 vcc, v36, v239
	v_addc_co_u32 v38, vcc, 0, v38, vcc
	s_nop 0
	v_cmp_le_u32 vcc, v36, v227
	v_addc_co_u32 v38, vcc, 0, v38, vcc
	s_nop 0
	v_cmp_le_u32 vcc, v36, v253
	v_addc_co_u32 v38, vcc, 0, v38, vcc
	s_nop 0
	v_cmp_le_u32 vcc, v36, v252
	v_addc_co_u32 v38, vcc, 0, v38, vcc
	s_nop 0
	v_cmp_le_u32 vcc, v36, v251
	v_addc_co_u32 v38, vcc, 0, v38, vcc
	s_nop 0
	v_cmp_le_u32 vcc, v36, v250
	v_addc_co_u32 v38, vcc, 0, v38, vcc
	s_nop 0
	v_cmp_le_u32 vcc, v36, v249
	v_addc_co_u32 v38, vcc, 0, v38, vcc
	s_nop 0
	v_cmp_le_u32 vcc, v36, v248
	v_addc_co_u32 v38, vcc, 0, v38, vcc
	s_nop 0
	v_cmp_le_u32 vcc, v36, v247
	v_addc_co_u32 v38, vcc, 0, v38, vcc
	s_nop 0
	v_cmp_le_u32 vcc, v36, v246
	v_addc_co_u32 v38, vcc, 0, v38, vcc
	s_nop 0
	v_cmp_le_u32 vcc, v36, v245
	v_addc_co_u32 v38, vcc, 0, v38, vcc
	s_nop 0
	v_cmp_le_u32 vcc, v36, v244
	v_addc_co_u32 v38, vcc, 0, v38, vcc
	s_nop 0
	v_cmp_le_u32 vcc, v36, v233
	v_addc_co_u32 v38, vcc, 0, v38, vcc
	s_nop 0
	v_cmp_le_u32 vcc, v36, v232
	v_addc_co_u32 v38, vcc, 0, v38, vcc
	s_nop 0
	v_cmp_le_u32 vcc, v36, v0
	v_addc_co_u32 v38, vcc, 0, v38, vcc
	s_nop 0
	v_cmp_le_u32 vcc, v36, v83
	v_addc_co_u32 v38, vcc, 0, v38, vcc
	s_nop 0
	v_cmp_le_u32 vcc, v36, v81
	v_addc_co_u32 v38, vcc, 0, v38, vcc
	s_nop 0
	v_cmp_le_u32 vcc, v36, v87
	v_addc_co_u32 v38, vcc, 0, v38, vcc
	s_nop 0
	v_cmp_le_u32 vcc, v36, v85
	v_addc_co_u32 v38, vcc, 0, v38, vcc
	s_nop 0
	v_cmp_le_u32 vcc, v36, v91
	v_addc_co_u32 v38, vcc, 0, v38, vcc
	s_nop 0
	v_cmp_le_u32 vcc, v36, v89
	v_addc_co_u32 v38, vcc, 0, v38, vcc
	s_nop 0
	v_cmp_le_u32 vcc, v36, v95
	v_addc_co_u32 v38, vcc, 0, v38, vcc
	s_nop 0
	v_cmp_le_u32 vcc, v36, v93
	v_addc_co_u32 v38, vcc, 0, v38, vcc
	s_nop 0
	v_cmp_le_u32 vcc, v36, v99
; DI int shflxi(int v, int m, int lane) { return __builtin_amdgcn_ds_bpermute((lane ^ m) << 2, v); }
; DI int wave_sum_i(int v, int lane) {
; #pragma unroll
;   for (int o = 32; o > 0; o >>= 1) v += shflxi(v, o, lane);
;   return v;
; }
; template <int NJ>
; DI void select_row(const float* row, int n, u64* bmrow, int lane) {
;     ...
;   while (!exact && hi - lo > 1u) {
;     const unsigned cand = lo + ((hi - lo) >> 1);
;     int c = 0;
; #pragma unroll
;     for (int jj = 0; jj < NJ; ++jj)
;       asm volatile("v_cmp_le_u32 vcc, %1, %2\n\tv_addc_co_u32 %0, vcc, 0, %0, vcc" : "+v"(c) : "s"(cand), "v"(key[jj]) : "vcc");
;     c = wave_sum_i(c, lane);
;     if (c == 256) { T = cand; exact = true; }
;     else if (c > 256) lo = cand; else hi = cand;
;   }
	v_addc_co_u32 v38, vcc, 0, v38, vcc
	s_nop 0
	v_cmp_le_u32 vcc, v36, v97
	v_addc_co_u32 v38, vcc, 0, v38, vcc
	s_nop 0
	v_cmp_le_u32 vcc, v36, v103
	v_addc_co_u32 v38, vcc, 0, v38, vcc
	s_nop 0
	v_cmp_le_u32 vcc, v36, v101
	v_addc_co_u32 v38, vcc, 0, v38, vcc
	s_nop 0
	v_cmp_le_u32 vcc, v36, v107
	v_addc_co_u32 v38, vcc, 0, v38, vcc
	s_nop 0
	v_cmp_le_u32 vcc, v36, v105
	v_addc_co_u32 v38, vcc, 0, v38, vcc
	s_nop 0
	v_cmp_le_u32 vcc, v36, v111
	v_addc_co_u32 v38, vcc, 0, v38, vcc
	s_nop 0
	v_cmp_le_u32 vcc, v36, v109
	v_addc_co_u32 v38, vcc, 0, v38, vcc
	s_nop 0
	v_cmp_le_u32 vcc, v36, v115
	v_addc_co_u32 v38, vcc, 0, v38, vcc
	s_nop 0
	v_cmp_le_u32 vcc, v36, v113
	v_addc_co_u32 v38, vcc, 0, v38, vcc
	s_nop 0
	v_cmp_le_u32 vcc, v36, v119
	v_addc_co_u32 v38, vcc, 0, v38, vcc
	s_nop 0
	v_cmp_le_u32 vcc, v36, v117
	v_addc_co_u32 v38, vcc, 0, v38, vcc
	s_nop 0
	v_cmp_le_u32 vcc, v36, v123
	v_addc_co_u32 v38, vcc, 0, v38, vcc
	s_nop 0
	v_cmp_le_u32 vcc, v36, v121
	v_addc_co_u32 v38, vcc, 0, v38, vcc
	s_nop 0
	v_cmp_le_u32 vcc, v36, v127
	v_addc_co_u32 v38, vcc, 0, v38, vcc
	s_nop 0
	v_cmp_le_u32 vcc, v36, v125
	v_addc_co_u32 v38, vcc, 0, v38, vcc
	s_nop 0
	v_cmp_le_u32 vcc, v36, v131
	v_addc_co_u32 v38, vcc, 0, v38, vcc
	s_nop 0
	v_cmp_le_u32 vcc, v36, v129
	v_addc_co_u32 v38, vcc, 0, v38, vcc
	s_nop 0
	v_cmp_le_u32 vcc, v36, v135
	v_addc_co_u32 v38, vcc, 0, v38, vcc
	s_nop 0
	v_cmp_le_u32 vcc, v36, v133
	v_addc_co_u32 v38, vcc, 0, v38, vcc
	s_nop 0
	v_cmp_le_u32 vcc, v36, v139
	v_addc_co_u32 v38, vcc, 0, v38, vcc
	s_nop 0
	v_cmp_le_u32 vcc, v36, v137
	v_addc_co_u32 v38, vcc, 0, v38, vcc
	s_nop 0
	v_cmp_le_u32 vcc, v36, v143
	v_addc_co_u32 v38, vcc, 0, v38, vcc
	s_nop 0
	v_cmp_le_u32 vcc, v36, v141
	v_addc_co_u32 v38, vcc, 0, v38, vcc
	s_nop 0
	v_cmp_le_u32 vcc, v36, v147
	v_addc_co_u32 v38, vcc, 0, v38, vcc
	s_nop 0
	v_cmp_le_u32 vcc, v36, v145
	v_addc_co_u32 v38, vcc, 0, v38, vcc
	s_nop 0
	v_cmp_le_u32 vcc, v36, v151
	v_addc_co_u32 v38, vcc, 0, v38, vcc
	s_nop 0
	v_cmp_le_u32 vcc, v36, v149
	v_addc_co_u32 v38, vcc, 0, v38, vcc
	s_nop 0
	v_cmp_le_u32 vcc, v36, v155
	v_addc_co_u32 v38, vcc, 0, v38, vcc
	s_nop 0
	v_cmp_le_u32 vcc, v36, v153
	v_addc_co_u32 v38, vcc, 0, v38, vcc
	s_nop 0
	v_cmp_le_u32 vcc, v36, v159
	v_addc_co_u32 v38, vcc, 0, v38, vcc
	s_nop 0
	v_cmp_le_u32 vcc, v36, v157
	v_addc_co_u32 v38, vcc, 0, v38, vcc
	s_nop 0
	v_cmp_le_u32 vcc, v36, v163
	v_addc_co_u32 v38, vcc, 0, v38, vcc
	s_nop 0
	v_cmp_le_u32 vcc, v36, v161
	v_addc_co_u32 v38, vcc, 0, v38, vcc
	s_nop 0
	v_cmp_le_u32 vcc, v36, v167
	v_addc_co_u32 v38, vcc, 0, v38, vcc
	s_nop 0
	v_cmp_le_u32 vcc, v36, v165
	v_addc_co_u32 v38, vcc, 0, v38, vcc
	s_nop 0
	v_cmp_le_u32 vcc, v36, v171
	v_addc_co_u32 v38, vcc, 0, v38, vcc
	s_nop 0
	v_cmp_le_u32 vcc, v36, v169
	v_addc_co_u32 v38, vcc, 0, v38, vcc
	s_nop 0
	v_cmp_le_u32 vcc, v36, v175
	v_addc_co_u32 v38, vcc, 0, v38, vcc
	s_nop 0
	v_cmp_le_u32 vcc, v36, v173
	v_addc_co_u32 v38, vcc, 0, v38, vcc
	s_nop 0
	v_cmp_le_u32 vcc, v36, v179
	v_addc_co_u32 v38, vcc, 0, v38, vcc
	s_nop 0
	v_cmp_le_u32 vcc, v36, v177
	v_addc_co_u32 v38, vcc, 0, v38, vcc
	s_nop 0
	v_cmp_le_u32 vcc, v36, v183
	v_addc_co_u32 v38, vcc, 0, v38, vcc
	s_nop 0
	v_cmp_le_u32 vcc, v36, v181
	v_addc_co_u32 v38, vcc, 0, v38, vcc
	s_nop 0
	v_cmp_le_u32 vcc, v36, v187
	v_addc_co_u32 v38, vcc, 0, v38, vcc
	s_nop 0
	v_cmp_le_u32 vcc, v36, v185
	v_addc_co_u32 v38, vcc, 0, v38, vcc
	s_nop 0
	v_cmp_le_u32 vcc, v36, v191
	v_addc_co_u32 v38, vcc, 0, v38, vcc
	s_nop 0
	v_cmp_le_u32 vcc, v36, v189
	v_addc_co_u32 v38, vcc, 0, v38, vcc
	s_nop 0
	v_cmp_le_u32 vcc, v36, v195
	v_addc_co_u32 v38, vcc, 0, v38, vcc
	s_nop 0
	v_cmp_le_u32 vcc, v36, v193
	v_addc_co_u32 v38, vcc, 0, v38, vcc
	s_nop 0
	v_cmp_le_u32 vcc, v36, v199
	v_addc_co_u32 v38, vcc, 0, v38, vcc
	s_nop 0
	v_cmp_le_u32 vcc, v36, v197
	v_addc_co_u32 v38, vcc, 0, v38, vcc
	s_nop 0
	v_cmp_le_u32 vcc, v36, v235
	v_addc_co_u32 v38, vcc, 0, v38, vcc
	s_nop 0
	v_cmp_le_u32 vcc, v36, v234
	v_addc_co_u32 v38, vcc, 0, v38, vcc
	s_nop 0
	v_cmp_le_u32 vcc, v36, v243
	v_addc_co_u32 v38, vcc, 0, v38, vcc
	s_nop 0
	v_cmp_le_u32 vcc, v36, v242
	v_addc_co_u32 v38, vcc, 0, v38, vcc
	s_nop 1
	v_add_u32_dpp v38, v38, v38 row_shr:1 row_mask:0xf bank_mask:0xf bound_ctrl:0
	s_nop 1
	v_add_u32_dpp v38, v38, v38 row_shr:2 row_mask:0xf bank_mask:0xf bound_ctrl:0
	s_nop 1
	v_add_u32_dpp v38, v38, v38 row_shr:4 row_mask:0xf bank_mask:0xf bound_ctrl:0
	s_nop 1
	v_add_u32_dpp v38, v38, v38 row_shr:8 row_mask:0xf bank_mask:0xf bound_ctrl:0
	s_nop 1
	v_add_u32_dpp v38, v38, v38 row_bcast:15 row_mask:0xa bank_mask:0xf
	s_nop 1
	v_add_u32_dpp v38, v38, v38 row_bcast:31 row_mask:0xc bank_mask:0xf
	s_nop 1
	v_readlane_b32 s98, v38, 63
	s_nop 1
	v_mov_b32_e32 v38, s98
	v_cmp_lt_i32_e32 vcc, s38, v38
	s_nop 1
	v_cndmask_b32_e32 v40, v230, v36, vcc
	v_cmp_lt_i32_e32 vcc, s39, v38
	s_nop 1
	v_cndmask_b32_e32 v34, v36, v34, vcc
	v_cmp_eq_u32_e32 vcc, s38, v38
	s_nop 1
	v_cndmask_b32_e32 v230, v40, v230, vcc
	v_cndmask_b32_e32 v32, v32, v36, vcc
	v_sub_u32_e32 v36, v34, v230
	v_cmp_gt_u32_e64 s[6:7], 2, v36
	s_or_b64 s[6:7], vcc, s[6:7]
	s_and_b64 s[6:7], exec, s[6:7]
	s_or_b64 s[24:25], s[6:7], s[24:25]
	s_andn2_b64 s[6:7], s[26:27], exec
	s_and_b64 s[26:27], vcc, exec
	s_or_b64 s[26:27], s[6:7], s[26:27]
	s_andn2_b64 exec, exec, s[24:25]
	s_cbranch_execnz .LBB0_644
	s_or_b64 exec, exec, s[24:25]
	s_andn2_b64 s[6:7], s[20:21], exec
	s_and_b64 s[20:21], s[26:27], exec
	s_or_b64 s[20:21], s[6:7], s[20:21]

; template <int NJ>
; DI void select_row(const float* row, int n, u64* bmrow, int lane) {
;     ...
;         const unsigned cand = X | (1u << bit);
;         int c = 0;
; #pragma unroll
;         for (int jj = 0; jj < NJ; ++jj) {
;           unsigned tmp;
;           asm volatile("v_add_u32 %1, %7, %5\n\tv_cmp_eq_u32 vcc, %2, %3\n\tv_cndmask_b32 %1, %4, %1, vcc\n\tv_cmp_gt_u32 vcc, %6, %1\n\tv_addc_co_u32 %0, vcc, 0, %0, vcc"
;                        : "+v"(c), "=&v"(tmp) : "s"(T), "v"(key[jj]), "v"(bigv), "v"(lane), "s"(cand), "n"(jj * 64) : "vcc");
;         }
;         c = wave_sum_i(c, lane);
;         if (c <= need) X = cand;
;       }
.LBB0_649:
	v_mov_b32_e32 v38, v1
	v_lshl_or_b32 v231, 1, s22, v34
	v_add_u32 v40, 0, v2
	v_cmp_eq_u32 vcc, v230, v79
	v_cndmask_b32 v40, v36, v40, vcc
	v_cmp_gt_u32 vcc, v231, v40
	v_addc_co_u32 v38, vcc, 0, v38, vcc
	s_add_i32 s22, s22, -1
	v_add_u32 v40, 64, v2
	v_cmp_eq_u32 vcc, v230, v77
	v_cndmask_b32 v40, v36, v40, vcc
	v_cmp_gt_u32 vcc, v231, v40
	v_addc_co_u32 v38, vcc, 0, v38, vcc
	s_cmp_lg_u32 s22, -1
	v_add_u32 v40, 0x80, v2
	v_cmp_eq_u32 vcc, v230, v75
	v_cndmask_b32 v40, v36, v40, vcc
	v_cmp_gt_u32 vcc, v231, v40
	v_addc_co_u32 v38, vcc, 0, v38, vcc
	s_nop 0
	v_add_u32 v40, 0xc0, v2
	v_cmp_eq_u32 vcc, v230, v73
	v_cndmask_b32 v40, v36, v40, vcc
	v_cmp_gt_u32 vcc, v231, v40
	v_addc_co_u32 v38, vcc, 0, v38, vcc
	s_nop 0
	v_add_u32 v40, 0x100, v2
	v_cmp_eq_u32 vcc, v230, v71
	v_cndmask_b32 v40, v36, v40, vcc
	v_cmp_gt_u32 vcc, v231, v40
	v_addc_co_u32 v38, vcc, 0, v38, vcc
	s_nop 0
	v_add_u32 v40, 0x140, v2
	v_cmp_eq_u32 vcc, v230, v69
	v_cndmask_b32 v40, v36, v40, vcc
	v_cmp_gt_u32 vcc, v231, v40
	v_addc_co_u32 v38, vcc, 0, v38, vcc
	s_nop 0
	v_add_u32 v40, 0x180, v2
	v_cmp_eq_u32 vcc, v230, v67
	v_cndmask_b32 v40, v36, v40, vcc
	v_cmp_gt_u32 vcc, v231, v40
	v_addc_co_u32 v38, vcc, 0, v38, vcc
	s_nop 0
	v_add_u32 v40, 0x1c0, v2
	v_cmp_eq_u32 vcc, v230, v65
	v_cndmask_b32 v40, v36, v40, vcc
	v_cmp_gt_u32 vcc, v231, v40
	v_addc_co_u32 v38, vcc, 0, v38, vcc
	s_nop 0
	v_add_u32 v40, 0x200, v2
	v_cmp_eq_u32 vcc, v230, v63
	v_cndmask_b32 v40, v36, v40, vcc
	v_cmp_gt_u32 vcc, v231, v40
	v_addc_co_u32 v38, vcc, 0, v38, vcc
	s_nop 0
	v_add_u32 v40, 0x240, v2
	v_cmp_eq_u32 vcc, v230, v61
	v_cndmask_b32 v40, v36, v40, vcc
	v_cmp_gt_u32 vcc, v231, v40
	v_addc_co_u32 v38, vcc, 0, v38, vcc
	s_nop 0
	v_add_u32 v40, 0x280, v2
	v_cmp_eq_u32 vcc, v230, v59
	v_cndmask_b32 v40, v36, v40, vcc
	v_cmp_gt_u32 vcc, v231, v40
	v_addc_co_u32 v38, vcc, 0, v38, vcc
	s_nop 0
	v_add_u32 v40, 0x2c0, v2
	v_cmp_eq_u32 vcc, v230, v57
	v_cndmask_b32 v40, v36, v40, vcc
	v_cmp_gt_u32 vcc, v231, v40
	v_addc_co_u32 v38, vcc, 0, v38, vcc
	s_nop 0
	v_add_u32 v40, 0x300, v2
	v_cmp_eq_u32 vcc, v230, v55
	v_cndmask_b32 v40, v36, v40, vcc
	v_cmp_gt_u32 vcc, v231, v40
	v_addc_co_u32 v38, vcc, 0, v38, vcc
	s_nop 0
	v_add_u32 v40, 0x340, v2
	v_cmp_eq_u32 vcc, v230, v51
	v_cndmask_b32 v40, v36, v40, vcc
	v_cmp_gt_u32 vcc, v231, v40
	v_addc_co_u32 v38, vcc, 0, v38, vcc
	s_nop 0
	v_add_u32 v40, 0x380, v2
	v_cmp_eq_u32 vcc, v230, v53
	v_cndmask_b32 v40, v36, v40, vcc
	v_cmp_gt_u32 vcc, v231, v40
	v_addc_co_u32 v38, vcc, 0, v38, vcc
	s_nop 0
	v_add_u32 v40, 0x3c0, v2
	v_cmp_eq_u32 vcc, v230, v49
	v_cndmask_b32 v40, v36, v40, vcc
	v_cmp_gt_u32 vcc, v231, v40
	v_addc_co_u32 v38, vcc, 0, v38, vcc
	s_nop 0
	v_add_u32 v40, 0x400, v2
	v_cmp_eq_u32 vcc, v230, v47
	v_cndmask_b32 v40, v36, v40, vcc
	v_cmp_gt_u32 vcc, v231, v40
	v_addc_co_u32 v38, vcc, 0, v38, vcc
	s_nop 0
	v_add_u32 v40, 0x440, v2
	v_cmp_eq_u32 vcc, v230, v45
	v_cndmask_b32 v40, v36, v40, vcc
	v_cmp_gt_u32 vcc, v231, v40
	v_addc_co_u32 v38, vcc, 0, v38, vcc
	s_nop 0
	v_add_u32 v40, 0x480, v2
	v_cmp_eq_u32 vcc, v230, v43
	v_cndmask_b32 v40, v36, v40, vcc
	v_cmp_gt_u32 vcc, v231, v40
	v_addc_co_u32 v38, vcc, 0, v38, vcc
	s_nop 0
	v_add_u32 v40, 0x4c0, v2
	v_cmp_eq_u32 vcc, v230, v41
	v_cndmask_b32 v40, v36, v40, vcc
	v_cmp_gt_u32 vcc, v231, v40
	v_addc_co_u32 v38, vcc, 0, v38, vcc
	s_nop 0
	v_add_u32 v40, 0x500, v2
	v_cmp_eq_u32 vcc, v230, v39
	v_cndmask_b32 v40, v36, v40, vcc
	v_cmp_gt_u32 vcc, v231, v40
	v_addc_co_u32 v38, vcc, 0, v38, vcc
	s_nop 0
	v_add_u32 v40, 0x540, v2
	v_cmp_eq_u32 vcc, v230, v37
	v_cndmask_b32 v40, v36, v40, vcc
	v_cmp_gt_u32 vcc, v231, v40
	v_addc_co_u32 v38, vcc, 0, v38, vcc
	s_nop 0
	v_add_u32 v40, 0x580, v2
	v_cmp_eq_u32 vcc, v230, v35
	v_cndmask_b32 v40, v36, v40, vcc
	v_cmp_gt_u32 vcc, v231, v40
	v_addc_co_u32 v38, vcc, 0, v38, vcc
	s_nop 0
	v_add_u32 v40, 0x5c0, v2
	v_cmp_eq_u32 vcc, v230, v33
	v_cndmask_b32 v40, v36, v40, vcc
	v_cmp_gt_u32 vcc, v231, v40
	v_addc_co_u32 v38, vcc, 0, v38, vcc
	s_nop 0
	v_add_u32 v40, 0x600, v2
	v_cmp_eq_u32 vcc, v230, v31
	v_cndmask_b32 v40, v36, v40, vcc
	v_cmp_gt_u32 vcc, v231, v40
	v_addc_co_u32 v38, vcc, 0, v38, vcc
	s_nop 0
	v_add_u32 v40, 0x640, v2
	v_cmp_eq_u32 vcc, v230, v29
	v_cndmask_b32 v40, v36, v40, vcc
	v_cmp_gt_u32 vcc, v231, v40
	v_addc_co_u32 v38, vcc, 0, v38, vcc
	s_nop 0
	v_add_u32 v40, 0x680, v2
	v_cmp_eq_u32 vcc, v230, v27
	v_cndmask_b32 v40, v36, v40, vcc
	v_cmp_gt_u32 vcc, v231, v40
	v_addc_co_u32 v38, vcc, 0, v38, vcc
	s_nop 0
	v_add_u32 v40, 0x6c0, v2
	v_cmp_eq_u32 vcc, v230, v25
	v_cndmask_b32 v40, v36, v40, vcc
	v_cmp_gt_u32 vcc, v231, v40
	v_addc_co_u32 v38, vcc, 0, v38, vcc
	s_nop 0
	v_add_u32 v40, 0x700, v2
	v_cmp_eq_u32 vcc, v230, v23
	v_cndmask_b32 v40, v36, v40, vcc
	v_cmp_gt_u32 vcc, v231, v40
	v_addc_co_u32 v38, vcc, 0, v38, vcc
	s_nop 0
	v_add_u32 v40, 0x740, v2
	v_cmp_eq_u32 vcc, v230, v21
	v_cndmask_b32 v40, v36, v40, vcc
	v_cmp_gt_u32 vcc, v231, v40
	v_addc_co_u32 v38, vcc, 0, v38, vcc
	s_nop 0
	v_add_u32 v40, 0x780, v2
	v_cmp_eq_u32 vcc, v230, v19
	v_cndmask_b32 v40, v36, v40, vcc
	v_cmp_gt_u32 vcc, v231, v40
	v_addc_co_u32 v38, vcc, 0, v38, vcc
	s_nop 0
	v_add_u32 v40, 0x7c0, v2
	v_cmp_eq_u32 vcc, v230, v17
	v_cndmask_b32 v40, v36, v40, vcc
	v_cmp_gt_u32 vcc, v231, v40
	v_addc_co_u32 v38, vcc, 0, v38, vcc
	s_nop 0
	v_add_u32 v40, 0x800, v2
	v_cmp_eq_u32 vcc, v230, v30
	v_cndmask_b32 v40, v36, v40, vcc
	v_cmp_gt_u32 vcc, v231, v40
	v_addc_co_u32 v38, vcc, 0, v38, vcc
	s_nop 0
	v_add_u32 v40, 0x840, v2
	v_cmp_eq_u32 vcc, v230, v28
	v_cndmask_b32 v40, v36, v40, vcc
	v_cmp_gt_u32 vcc, v231, v40
	v_addc_co_u32 v38, vcc, 0, v38, vcc
; template <int NJ>
; DI void select_row(const float* row, int n, u64* bmrow, int lane) {
;     ...
;         const unsigned cand = X | (1u << bit);
;         int c = 0;
; #pragma unroll
;         for (int jj = 0; jj < NJ; ++jj) {
;           unsigned tmp;
;           asm volatile("v_add_u32 %1, %7, %5\n\tv_cmp_eq_u32 vcc, %2, %3\n\tv_cndmask_b32 %1, %4, %1, vcc\n\tv_cmp_gt_u32 vcc, %6, %1\n\tv_addc_co_u32 %0, vcc, 0, %0, vcc"
;                        : "+v"(c), "=&v"(tmp) : "s"(T), "v"(key[jj]), "v"(bigv), "v"(lane), "s"(cand), "n"(jj * 64) : "vcc");
;         }
;         c = wave_sum_i(c, lane);
;         if (c <= need) X = cand;
;       }
	s_nop 0
	v_add_u32 v40, 0x880, v2
	v_cmp_eq_u32 vcc, v230, v26
	v_cndmask_b32 v40, v36, v40, vcc
	v_cmp_gt_u32 vcc, v231, v40
	v_addc_co_u32 v38, vcc, 0, v38, vcc
	s_nop 0
	v_add_u32 v40, 0x8c0, v2
	v_cmp_eq_u32 vcc, v230, v24
	v_cndmask_b32 v40, v36, v40, vcc
	v_cmp_gt_u32 vcc, v231, v40
	v_addc_co_u32 v38, vcc, 0, v38, vcc
	s_nop 0
	v_add_u32 v40, 0x900, v2
	v_cmp_eq_u32 vcc, v230, v22
	v_cndmask_b32 v40, v36, v40, vcc
	v_cmp_gt_u32 vcc, v231, v40
	v_addc_co_u32 v38, vcc, 0, v38, vcc
	s_nop 0
	v_add_u32 v40, 0x940, v2
	v_cmp_eq_u32 vcc, v230, v20
	v_cndmask_b32 v40, v36, v40, vcc
	v_cmp_gt_u32 vcc, v231, v40
	v_addc_co_u32 v38, vcc, 0, v38, vcc
	s_nop 0
	v_add_u32 v40, 0x980, v2
	v_cmp_eq_u32 vcc, v230, v18
	v_cndmask_b32 v40, v36, v40, vcc
	v_cmp_gt_u32 vcc, v231, v40
	v_addc_co_u32 v38, vcc, 0, v38, vcc
	s_nop 0
	v_add_u32 v40, 0x9c0, v2
	v_cmp_eq_u32 vcc, v230, v16
	v_cndmask_b32 v40, v36, v40, vcc
	v_cmp_gt_u32 vcc, v231, v40
	v_addc_co_u32 v38, vcc, 0, v38, vcc
	s_nop 0
	v_add_u32 v40, 0xa00, v2
	v_cmp_eq_u32 vcc, v230, v14
	v_cndmask_b32 v40, v36, v40, vcc
	v_cmp_gt_u32 vcc, v231, v40
	v_addc_co_u32 v38, vcc, 0, v38, vcc
	s_nop 0
	v_add_u32 v40, 0xa40, v2
	v_cmp_eq_u32 vcc, v230, v12
	v_cndmask_b32 v40, v36, v40, vcc
	v_cmp_gt_u32 vcc, v231, v40
	v_addc_co_u32 v38, vcc, 0, v38, vcc
	s_nop 0
	v_add_u32 v40, 0xa80, v2
	v_cmp_eq_u32 vcc, v230, v10
	v_cndmask_b32 v40, v36, v40, vcc
	v_cmp_gt_u32 vcc, v231, v40
	v_addc_co_u32 v38, vcc, 0, v38, vcc
	s_nop 0
	v_add_u32 v40, 0xac0, v2
	v_cmp_eq_u32 vcc, v230, v8
	v_cndmask_b32 v40, v36, v40, vcc
	v_cmp_gt_u32 vcc, v231, v40
	v_addc_co_u32 v38, vcc, 0, v38, vcc
	s_nop 0
	v_add_u32 v40, 0xb00, v2
	v_cmp_eq_u32 vcc, v230, v6
	v_cndmask_b32 v40, v36, v40, vcc
	v_cmp_gt_u32 vcc, v231, v40
	v_addc_co_u32 v38, vcc, 0, v38, vcc
	s_nop 0
	v_add_u32 v40, 0xb40, v2
	v_cmp_eq_u32 vcc, v230, v4
	v_cndmask_b32 v40, v36, v40, vcc
	v_cmp_gt_u32 vcc, v231, v40
	v_addc_co_u32 v38, vcc, 0, v38, vcc
	s_nop 0
	v_add_u32 v40, 0xb80, v2
	v_cmp_eq_u32 vcc, v230, v240
	v_cndmask_b32 v40, v36, v40, vcc
	v_cmp_gt_u32 vcc, v231, v40
	v_addc_co_u32 v38, vcc, 0, v38, vcc
	s_nop 0
	v_add_u32 v40, 0xbc0, v2
	v_cmp_eq_u32 vcc, v230, v236
	v_cndmask_b32 v40, v36, v40, vcc
	v_cmp_gt_u32 vcc, v231, v40
	v_addc_co_u32 v38, vcc, 0, v38, vcc
	s_nop 0
	v_add_u32 v40, 0xc00, v2
	v_cmp_eq_u32 vcc, v230, v211
	v_cndmask_b32 v40, v36, v40, vcc
	v_cmp_gt_u32 vcc, v231, v40
	v_addc_co_u32 v38, vcc, 0, v38, vcc
	s_nop 0
	v_add_u32 v40, 0xc40, v2
	v_cmp_eq_u32 vcc, v230, v239
	v_cndmask_b32 v40, v36, v40, vcc
	v_cmp_gt_u32 vcc, v231, v40
	v_addc_co_u32 v38, vcc, 0, v38, vcc
	s_nop 0
	v_add_u32 v40, 0xc80, v2
	v_cmp_eq_u32 vcc, v230, v227
	v_cndmask_b32 v40, v36, v40, vcc
	v_cmp_gt_u32 vcc, v231, v40
	v_addc_co_u32 v38, vcc, 0, v38, vcc
	s_nop 0
	v_add_u32 v40, 0xcc0, v2
	v_cmp_eq_u32 vcc, v230, v253
	v_cndmask_b32 v40, v36, v40, vcc
	v_cmp_gt_u32 vcc, v231, v40
	v_addc_co_u32 v38, vcc, 0, v38, vcc
	s_nop 0
	v_add_u32 v40, 0xd00, v2
	v_cmp_eq_u32 vcc, v230, v252
	v_cndmask_b32 v40, v36, v40, vcc
	v_cmp_gt_u32 vcc, v231, v40
	v_addc_co_u32 v38, vcc, 0, v38, vcc
	s_nop 0
	v_add_u32 v40, 0xd40, v2
	v_cmp_eq_u32 vcc, v230, v251
	v_cndmask_b32 v40, v36, v40, vcc
	v_cmp_gt_u32 vcc, v231, v40
	v_addc_co_u32 v38, vcc, 0, v38, vcc
	s_nop 0
	v_add_u32 v40, 0xd80, v2
	v_cmp_eq_u32 vcc, v230, v250
	v_cndmask_b32 v40, v36, v40, vcc
	v_cmp_gt_u32 vcc, v231, v40
	v_addc_co_u32 v38, vcc, 0, v38, vcc
	s_nop 0
	v_add_u32 v40, 0xdc0, v2
	v_cmp_eq_u32 vcc, v230, v249
	v_cndmask_b32 v40, v36, v40, vcc
	v_cmp_gt_u32 vcc, v231, v40
	v_addc_co_u32 v38, vcc, 0, v38, vcc
	s_nop 0
	v_add_u32 v40, 0xe00, v2
	v_cmp_eq_u32 vcc, v230, v248
	v_cndmask_b32 v40, v36, v40, vcc
	v_cmp_gt_u32 vcc, v231, v40
	v_addc_co_u32 v38, vcc, 0, v38, vcc
	s_nop 0
	v_add_u32 v40, 0xe40, v2
	v_cmp_eq_u32 vcc, v230, v247
	v_cndmask_b32 v40, v36, v40, vcc
	v_cmp_gt_u32 vcc, v231, v40
	v_addc_co_u32 v38, vcc, 0, v38, vcc
	s_nop 0
	v_add_u32 v40, 0xe80, v2
	v_cmp_eq_u32 vcc, v230, v246
	v_cndmask_b32 v40, v36, v40, vcc
	v_cmp_gt_u32 vcc, v231, v40
	v_addc_co_u32 v38, vcc, 0, v38, vcc
	s_nop 0
	v_add_u32 v40, 0xec0, v2
	v_cmp_eq_u32 vcc, v230, v245
	v_cndmask_b32 v40, v36, v40, vcc
	v_cmp_gt_u32 vcc, v231, v40
	v_addc_co_u32 v38, vcc, 0, v38, vcc
	s_nop 0
	v_add_u32 v40, 0xf00, v2
	v_cmp_eq_u32 vcc, v230, v244
	v_cndmask_b32 v40, v36, v40, vcc
	v_cmp_gt_u32 vcc, v231, v40
	v_addc_co_u32 v38, vcc, 0, v38, vcc
	s_nop 0
	v_add_u32 v40, 0xf40, v2
	v_cmp_eq_u32 vcc, v230, v233
	v_cndmask_b32 v40, v36, v40, vcc
	v_cmp_gt_u32 vcc, v231, v40
	v_addc_co_u32 v38, vcc, 0, v38, vcc
	s_nop 0
	v_add_u32 v40, 0xf80, v2
	v_cmp_eq_u32 vcc, v230, v232
	v_cndmask_b32 v40, v36, v40, vcc
	v_cmp_gt_u32 vcc, v231, v40
	v_addc_co_u32 v38, vcc, 0, v38, vcc
	s_nop 0
	v_add_u32 v40, 0xfc0, v2
	v_cmp_eq_u32 vcc, v230, v0
	v_cndmask_b32 v40, v36, v40, vcc
	v_cmp_gt_u32 vcc, v231, v40
	v_addc_co_u32 v38, vcc, 0, v38, vcc
	s_nop 0
	v_add_u32 v40, 0x1000, v2
	v_cmp_eq_u32 vcc, v230, v83
	v_cndmask_b32 v40, v36, v40, vcc
	v_cmp_gt_u32 vcc, v231, v40
	v_addc_co_u32 v38, vcc, 0, v38, vcc
	s_nop 0
	v_add_u32 v40, 0x1040, v2
	v_cmp_eq_u32 vcc, v230, v81
	v_cndmask_b32 v40, v36, v40, vcc
	v_cmp_gt_u32 vcc, v231, v40
	v_addc_co_u32 v38, vcc, 0, v38, vcc
	s_nop 0
	v_add_u32 v40, 0x1080, v2
	v_cmp_eq_u32 vcc, v230, v87
	v_cndmask_b32 v40, v36, v40, vcc
	v_cmp_gt_u32 vcc, v231, v40
	v_addc_co_u32 v38, vcc, 0, v38, vcc
	s_nop 0
	v_add_u32 v40, 0x10c0, v2
	v_cmp_eq_u32 vcc, v230, v85
	v_cndmask_b32 v40, v36, v40, vcc
	v_cmp_gt_u32 vcc, v231, v40
	v_addc_co_u32 v38, vcc, 0, v38, vcc
	s_nop 0
	v_add_u32 v40, 0x1100, v2
; template <int NJ>
; DI void select_row(const float* row, int n, u64* bmrow, int lane) {
;     ...
;         const unsigned cand = X | (1u << bit);
;         int c = 0;
; #pragma unroll
;         for (int jj = 0; jj < NJ; ++jj) {
;           unsigned tmp;
;           asm volatile("v_add_u32 %1, %7, %5\n\tv_cmp_eq_u32 vcc, %2, %3\n\tv_cndmask_b32 %1, %4, %1, vcc\n\tv_cmp_gt_u32 vcc, %6, %1\n\tv_addc_co_u32 %0, vcc, 0, %0, vcc"
;                        : "+v"(c), "=&v"(tmp) : "s"(T), "v"(key[jj]), "v"(bigv), "v"(lane), "s"(cand), "n"(jj * 64) : "vcc");
;         }
;         c = wave_sum_i(c, lane);
;         if (c <= need) X = cand;
;       }
	v_cmp_eq_u32 vcc, v230, v91
	v_cndmask_b32 v40, v36, v40, vcc
	v_cmp_gt_u32 vcc, v231, v40
	v_addc_co_u32 v38, vcc, 0, v38, vcc
	s_nop 0
	v_add_u32 v40, 0x1140, v2
	v_cmp_eq_u32 vcc, v230, v89
	v_cndmask_b32 v40, v36, v40, vcc
	v_cmp_gt_u32 vcc, v231, v40
	v_addc_co_u32 v38, vcc, 0, v38, vcc
	s_nop 0
	v_add_u32 v40, 0x1180, v2
	v_cmp_eq_u32 vcc, v230, v95
	v_cndmask_b32 v40, v36, v40, vcc
	v_cmp_gt_u32 vcc, v231, v40
	v_addc_co_u32 v38, vcc, 0, v38, vcc
	s_nop 0
	v_add_u32 v40, 0x11c0, v2
	v_cmp_eq_u32 vcc, v230, v93
	v_cndmask_b32 v40, v36, v40, vcc
	v_cmp_gt_u32 vcc, v231, v40
	v_addc_co_u32 v38, vcc, 0, v38, vcc
	s_nop 0
	v_add_u32 v40, 0x1200, v2
	v_cmp_eq_u32 vcc, v230, v99
	v_cndmask_b32 v40, v36, v40, vcc
	v_cmp_gt_u32 vcc, v231, v40
	v_addc_co_u32 v38, vcc, 0, v38, vcc
	s_nop 0
	v_add_u32 v40, 0x1240, v2
	v_cmp_eq_u32 vcc, v230, v97
	v_cndmask_b32 v40, v36, v40, vcc
	v_cmp_gt_u32 vcc, v231, v40
	v_addc_co_u32 v38, vcc, 0, v38, vcc
	s_nop 0
	v_add_u32 v40, 0x1280, v2
	v_cmp_eq_u32 vcc, v230, v103
	v_cndmask_b32 v40, v36, v40, vcc
	v_cmp_gt_u32 vcc, v231, v40
	v_addc_co_u32 v38, vcc, 0, v38, vcc
	s_nop 0
	v_add_u32 v40, 0x12c0, v2
	v_cmp_eq_u32 vcc, v230, v101
	v_cndmask_b32 v40, v36, v40, vcc
	v_cmp_gt_u32 vcc, v231, v40
	v_addc_co_u32 v38, vcc, 0, v38, vcc
	s_nop 0
	v_add_u32 v40, 0x1300, v2
	v_cmp_eq_u32 vcc, v230, v107
	v_cndmask_b32 v40, v36, v40, vcc
	v_cmp_gt_u32 vcc, v231, v40
	v_addc_co_u32 v38, vcc, 0, v38, vcc
	s_nop 0
	v_add_u32 v40, 0x1340, v2
	v_cmp_eq_u32 vcc, v230, v105
	v_cndmask_b32 v40, v36, v40, vcc
	v_cmp_gt_u32 vcc, v231, v40
	v_addc_co_u32 v38, vcc, 0, v38, vcc
	s_nop 0
	v_add_u32 v40, 0x1380, v2
	v_cmp_eq_u32 vcc, v230, v111
	v_cndmask_b32 v40, v36, v40, vcc
	v_cmp_gt_u32 vcc, v231, v40
	v_addc_co_u32 v38, vcc, 0, v38, vcc
	s_nop 0
	v_add_u32 v40, 0x13c0, v2
	v_cmp_eq_u32 vcc, v230, v109
	v_cndmask_b32 v40, v36, v40, vcc
	v_cmp_gt_u32 vcc, v231, v40
	v_addc_co_u32 v38, vcc, 0, v38, vcc
	s_nop 0
	v_add_u32 v40, 0x1400, v2
	v_cmp_eq_u32 vcc, v230, v115
	v_cndmask_b32 v40, v36, v40, vcc
	v_cmp_gt_u32 vcc, v231, v40
	v_addc_co_u32 v38, vcc, 0, v38, vcc
	s_nop 0
	v_add_u32 v40, 0x1440, v2
	v_cmp_eq_u32 vcc, v230, v113
	v_cndmask_b32 v40, v36, v40, vcc
	v_cmp_gt_u32 vcc, v231, v40
	v_addc_co_u32 v38, vcc, 0, v38, vcc
	s_nop 0
	v_add_u32 v40, 0x1480, v2
	v_cmp_eq_u32 vcc, v230, v119
	v_cndmask_b32 v40, v36, v40, vcc
	v_cmp_gt_u32 vcc, v231, v40
	v_addc_co_u32 v38, vcc, 0, v38, vcc
	s_nop 0
	v_add_u32 v40, 0x14c0, v2
	v_cmp_eq_u32 vcc, v230, v117
	v_cndmask_b32 v40, v36, v40, vcc
	v_cmp_gt_u32 vcc, v231, v40
	v_addc_co_u32 v38, vcc, 0, v38, vcc
	s_nop 0
	v_add_u32 v40, 0x1500, v2
	v_cmp_eq_u32 vcc, v230, v123
	v_cndmask_b32 v40, v36, v40, vcc
	v_cmp_gt_u32 vcc, v231, v40
	v_addc_co_u32 v38, vcc, 0, v38, vcc
	s_nop 0
	v_add_u32 v40, 0x1540, v2
	v_cmp_eq_u32 vcc, v230, v121
	v_cndmask_b32 v40, v36, v40, vcc
	v_cmp_gt_u32 vcc, v231, v40
	v_addc_co_u32 v38, vcc, 0, v38, vcc
	s_nop 0
	v_add_u32 v40, 0x1580, v2
	v_cmp_eq_u32 vcc, v230, v127
	v_cndmask_b32 v40, v36, v40, vcc
	v_cmp_gt_u32 vcc, v231, v40
	v_addc_co_u32 v38, vcc, 0, v38, vcc
	s_nop 0
	v_add_u32 v40, 0x15c0, v2
	v_cmp_eq_u32 vcc, v230, v125
	v_cndmask_b32 v40, v36, v40, vcc
	v_cmp_gt_u32 vcc, v231, v40
	v_addc_co_u32 v38, vcc, 0, v38, vcc
	s_nop 0
	v_add_u32 v40, 0x1600, v2
	v_cmp_eq_u32 vcc, v230, v131
	v_cndmask_b32 v40, v36, v40, vcc
	v_cmp_gt_u32 vcc, v231, v40
	v_addc_co_u32 v38, vcc, 0, v38, vcc
	s_nop 0
	v_add_u32 v40, 0x1640, v2
	v_cmp_eq_u32 vcc, v230, v129
	v_cndmask_b32 v40, v36, v40, vcc
	v_cmp_gt_u32 vcc, v231, v40
	v_addc_co_u32 v38, vcc, 0, v38, vcc
	s_nop 0
	v_add_u32 v40, 0x1680, v2
	v_cmp_eq_u32 vcc, v230, v135
	v_cndmask_b32 v40, v36, v40, vcc
	v_cmp_gt_u32 vcc, v231, v40
	v_addc_co_u32 v38, vcc, 0, v38, vcc
	s_nop 0
	v_add_u32 v40, 0x16c0, v2
	v_cmp_eq_u32 vcc, v230, v133
	v_cndmask_b32 v40, v36, v40, vcc
	v_cmp_gt_u32 vcc, v231, v40
	v_addc_co_u32 v38, vcc, 0, v38, vcc
	s_nop 0
	v_add_u32 v40, 0x1700, v2
	v_cmp_eq_u32 vcc, v230, v139
	v_cndmask_b32 v40, v36, v40, vcc
	v_cmp_gt_u32 vcc, v231, v40
	v_addc_co_u32 v38, vcc, 0, v38, vcc
	s_nop 0
	v_add_u32 v40, 0x1740, v2
	v_cmp_eq_u32 vcc, v230, v137
	v_cndmask_b32 v40, v36, v40, vcc
	v_cmp_gt_u32 vcc, v231, v40
	v_addc_co_u32 v38, vcc, 0, v38, vcc
	s_nop 0
	v_add_u32 v40, 0x1780, v2
	v_cmp_eq_u32 vcc, v230, v143
	v_cndmask_b32 v40, v36, v40, vcc
	v_cmp_gt_u32 vcc, v231, v40
	v_addc_co_u32 v38, vcc, 0, v38, vcc
	s_nop 0
	v_add_u32 v40, 0x17c0, v2
	v_cmp_eq_u32 vcc, v230, v141
	v_cndmask_b32 v40, v36, v40, vcc
	v_cmp_gt_u32 vcc, v231, v40
	v_addc_co_u32 v38, vcc, 0, v38, vcc
	s_nop 0
	v_add_u32 v40, 0x1800, v2
	v_cmp_eq_u32 vcc, v230, v147
	v_cndmask_b32 v40, v36, v40, vcc
	v_cmp_gt_u32 vcc, v231, v40
	v_addc_co_u32 v38, vcc, 0, v38, vcc
	s_nop 0
	v_add_u32 v40, 0x1840, v2
	v_cmp_eq_u32 vcc, v230, v145
	v_cndmask_b32 v40, v36, v40, vcc
	v_cmp_gt_u32 vcc, v231, v40
	v_addc_co_u32 v38, vcc, 0, v38, vcc
	s_nop 0
	v_add_u32 v40, 0x1880, v2
	v_cmp_eq_u32 vcc, v230, v151
	v_cndmask_b32 v40, v36, v40, vcc
	v_cmp_gt_u32 vcc, v231, v40
	v_addc_co_u32 v38, vcc, 0, v38, vcc
	s_nop 0
	v_add_u32 v40, 0x18c0, v2
	v_cmp_eq_u32 vcc, v230, v149
	v_cndmask_b32 v40, v36, v40, vcc
	v_cmp_gt_u32 vcc, v231, v40
	v_addc_co_u32 v38, vcc, 0, v38, vcc
	s_nop 0
	v_add_u32 v40, 0x1900, v2
; DI int shflxi(int v, int m, int lane) { return __builtin_amdgcn_ds_bpermute((lane ^ m) << 2, v); }
; DI int wave_sum_i(int v, int lane) {
; #pragma unroll
;   for (int o = 32; o > 0; o >>= 1) v += shflxi(v, o, lane);
;   return v;
; }
; template <int NJ>
; DI void select_row(const float* row, int n, u64* bmrow, int lane) {
;     ...
;         const unsigned cand = X | (1u << bit);
;         int c = 0;
; #pragma unroll
;         for (int jj = 0; jj < NJ; ++jj) {
;           unsigned tmp;
;           asm volatile("v_add_u32 %1, %7, %5\n\tv_cmp_eq_u32 vcc, %2, %3\n\tv_cndmask_b32 %1, %4, %1, vcc\n\tv_cmp_gt_u32 vcc, %6, %1\n\tv_addc_co_u32 %0, vcc, 0, %0, vcc"
;                        : "+v"(c), "=&v"(tmp) : "s"(T), "v"(key[jj]), "v"(bigv), "v"(lane), "s"(cand), "n"(jj * 64) : "vcc");
;         }
;         c = wave_sum_i(c, lane);
;         if (c <= need) X = cand;
;       }
	v_cmp_eq_u32 vcc, v230, v155
	v_cndmask_b32 v40, v36, v40, vcc
	v_cmp_gt_u32 vcc, v231, v40
	v_addc_co_u32 v38, vcc, 0, v38, vcc
	s_nop 0
	v_add_u32 v40, 0x1940, v2
	v_cmp_eq_u32 vcc, v230, v153
	v_cndmask_b32 v40, v36, v40, vcc
	v_cmp_gt_u32 vcc, v231, v40
	v_addc_co_u32 v38, vcc, 0, v38, vcc
	s_nop 0
	v_add_u32 v40, 0x1980, v2
	v_cmp_eq_u32 vcc, v230, v159
	v_cndmask_b32 v40, v36, v40, vcc
	v_cmp_gt_u32 vcc, v231, v40
	v_addc_co_u32 v38, vcc, 0, v38, vcc
	s_nop 0
	v_add_u32 v40, 0x19c0, v2
	v_cmp_eq_u32 vcc, v230, v157
	v_cndmask_b32 v40, v36, v40, vcc
	v_cmp_gt_u32 vcc, v231, v40
	v_addc_co_u32 v38, vcc, 0, v38, vcc
	s_nop 0
	v_add_u32 v40, 0x1a00, v2
	v_cmp_eq_u32 vcc, v230, v163
	v_cndmask_b32 v40, v36, v40, vcc
	v_cmp_gt_u32 vcc, v231, v40
	v_addc_co_u32 v38, vcc, 0, v38, vcc
	s_nop 0
	v_add_u32 v40, 0x1a40, v2
	v_cmp_eq_u32 vcc, v230, v161
	v_cndmask_b32 v40, v36, v40, vcc
	v_cmp_gt_u32 vcc, v231, v40
	v_addc_co_u32 v38, vcc, 0, v38, vcc
	s_nop 0
	v_add_u32 v40, 0x1a80, v2
	v_cmp_eq_u32 vcc, v230, v167
	v_cndmask_b32 v40, v36, v40, vcc
	v_cmp_gt_u32 vcc, v231, v40
	v_addc_co_u32 v38, vcc, 0, v38, vcc
	s_nop 0
	v_add_u32 v40, 0x1ac0, v2
	v_cmp_eq_u32 vcc, v230, v165
	v_cndmask_b32 v40, v36, v40, vcc
	v_cmp_gt_u32 vcc, v231, v40
	v_addc_co_u32 v38, vcc, 0, v38, vcc
	s_nop 0
	v_add_u32 v40, 0x1b00, v2
	v_cmp_eq_u32 vcc, v230, v171
	v_cndmask_b32 v40, v36, v40, vcc
	v_cmp_gt_u32 vcc, v231, v40
	v_addc_co_u32 v38, vcc, 0, v38, vcc
	s_nop 0
	v_add_u32 v40, 0x1b40, v2
	v_cmp_eq_u32 vcc, v230, v169
	v_cndmask_b32 v40, v36, v40, vcc
	v_cmp_gt_u32 vcc, v231, v40
	v_addc_co_u32 v38, vcc, 0, v38, vcc
	s_nop 0
	v_add_u32 v40, 0x1b80, v2
	v_cmp_eq_u32 vcc, v230, v175
	v_cndmask_b32 v40, v36, v40, vcc
	v_cmp_gt_u32 vcc, v231, v40
	v_addc_co_u32 v38, vcc, 0, v38, vcc
	s_nop 0
	v_add_u32 v40, 0x1bc0, v2
	v_cmp_eq_u32 vcc, v230, v173
	v_cndmask_b32 v40, v36, v40, vcc
	v_cmp_gt_u32 vcc, v231, v40
	v_addc_co_u32 v38, vcc, 0, v38, vcc
	s_nop 0
	v_add_u32 v40, 0x1c00, v2
	v_cmp_eq_u32 vcc, v230, v179
	v_cndmask_b32 v40, v36, v40, vcc
	v_cmp_gt_u32 vcc, v231, v40
	v_addc_co_u32 v38, vcc, 0, v38, vcc
	s_nop 0
	v_add_u32 v40, 0x1c40, v2
	v_cmp_eq_u32 vcc, v230, v177
	v_cndmask_b32 v40, v36, v40, vcc
	v_cmp_gt_u32 vcc, v231, v40
	v_addc_co_u32 v38, vcc, 0, v38, vcc
	s_nop 0
	v_add_u32 v40, 0x1c80, v2
	v_cmp_eq_u32 vcc, v230, v183
	v_cndmask_b32 v40, v36, v40, vcc
	v_cmp_gt_u32 vcc, v231, v40
	v_addc_co_u32 v38, vcc, 0, v38, vcc
	s_nop 0
	v_add_u32 v40, 0x1cc0, v2
	v_cmp_eq_u32 vcc, v230, v181
	v_cndmask_b32 v40, v36, v40, vcc
	v_cmp_gt_u32 vcc, v231, v40
	v_addc_co_u32 v38, vcc, 0, v38, vcc
	s_nop 0
	v_add_u32 v40, 0x1d00, v2
	v_cmp_eq_u32 vcc, v230, v187
	v_cndmask_b32 v40, v36, v40, vcc
	v_cmp_gt_u32 vcc, v231, v40
	v_addc_co_u32 v38, vcc, 0, v38, vcc
	s_nop 0
	v_add_u32 v40, 0x1d40, v2
	v_cmp_eq_u32 vcc, v230, v185
	v_cndmask_b32 v40, v36, v40, vcc
	v_cmp_gt_u32 vcc, v231, v40
	v_addc_co_u32 v38, vcc, 0, v38, vcc
	s_nop 0
	v_add_u32 v40, 0x1d80, v2
	v_cmp_eq_u32 vcc, v230, v191
	v_cndmask_b32 v40, v36, v40, vcc
	v_cmp_gt_u32 vcc, v231, v40
	v_addc_co_u32 v38, vcc, 0, v38, vcc
	s_nop 0
	v_add_u32 v40, 0x1dc0, v2
	v_cmp_eq_u32 vcc, v230, v189
	v_cndmask_b32 v40, v36, v40, vcc
	v_cmp_gt_u32 vcc, v231, v40
	v_addc_co_u32 v38, vcc, 0, v38, vcc
	s_nop 0
	v_add_u32 v40, 0x1e00, v2
	v_cmp_eq_u32 vcc, v230, v195
	v_cndmask_b32 v40, v36, v40, vcc
	v_cmp_gt_u32 vcc, v231, v40
	v_addc_co_u32 v38, vcc, 0, v38, vcc
	s_nop 0
	v_add_u32 v40, 0x1e40, v2
	v_cmp_eq_u32 vcc, v230, v193
	v_cndmask_b32 v40, v36, v40, vcc
	v_cmp_gt_u32 vcc, v231, v40
	v_addc_co_u32 v38, vcc, 0, v38, vcc
	s_nop 0
	v_add_u32 v40, 0x1e80, v2
	v_cmp_eq_u32 vcc, v230, v199
	v_cndmask_b32 v40, v36, v40, vcc
	v_cmp_gt_u32 vcc, v231, v40
	v_addc_co_u32 v38, vcc, 0, v38, vcc
	s_nop 0
	v_add_u32 v40, 0x1ec0, v2
	v_cmp_eq_u32 vcc, v230, v197
	v_cndmask_b32 v40, v36, v40, vcc
	v_cmp_gt_u32 vcc, v231, v40
	v_addc_co_u32 v38, vcc, 0, v38, vcc
	s_nop 0
	v_add_u32 v40, 0x1f00, v2
	v_cmp_eq_u32 vcc, v230, v235
	v_cndmask_b32 v40, v36, v40, vcc
	v_cmp_gt_u32 vcc, v231, v40
	v_addc_co_u32 v38, vcc, 0, v38, vcc
	s_nop 0
	v_add_u32 v40, 0x1f40, v2
	v_cmp_eq_u32 vcc, v230, v234
	v_cndmask_b32 v40, v36, v40, vcc
	v_cmp_gt_u32 vcc, v231, v40
	v_addc_co_u32 v38, vcc, 0, v38, vcc
	s_nop 0
	v_add_u32 v40, 0x1f80, v2
	v_cmp_eq_u32 vcc, v230, v243
	v_cndmask_b32 v40, v36, v40, vcc
	v_cmp_gt_u32 vcc, v231, v40
	v_addc_co_u32 v38, vcc, 0, v38, vcc
	s_nop 0
	v_add_u32 v40, 0x1fc0, v2
	v_cmp_eq_u32 vcc, v230, v242
	v_cndmask_b32 v40, v36, v40, vcc
	v_cmp_gt_u32 vcc, v231, v40
	v_addc_co_u32 v38, vcc, 0, v38, vcc
	s_nop 1
	v_add_u32_dpp v38, v38, v38 row_shr:1 row_mask:0xf bank_mask:0xf bound_ctrl:0
	s_nop 1
	v_add_u32_dpp v38, v38, v38 row_shr:2 row_mask:0xf bank_mask:0xf bound_ctrl:0
	s_nop 1
	v_add_u32_dpp v38, v38, v38 row_shr:4 row_mask:0xf bank_mask:0xf bound_ctrl:0
	s_nop 1
	v_add_u32_dpp v38, v38, v38 row_shr:8 row_mask:0xf bank_mask:0xf bound_ctrl:0
	s_nop 1
	v_add_u32_dpp v38, v38, v38 row_bcast:15 row_mask:0xa bank_mask:0xf
	s_nop 1
	v_add_u32_dpp v38, v38, v38 row_bcast:31 row_mask:0xc bank_mask:0xf
	s_nop 1
	v_readlane_b32 s98, v38, 63
	s_nop 1
	v_mov_b32_e32 v38, s98
	v_cmp_gt_i32_e32 vcc, v38, v32
	s_nop 1
	v_cndmask_b32_e32 v34, v231, v34, vcc
	s_cbranch_scc1 .LBB0_649

; DI int shflxi(int v, int m, int lane) { return __builtin_amdgcn_ds_bpermute((lane ^ m) << 2, v); }
; DI int wave_sum_i(int v, int lane) {
; #pragma unroll
;   for (int o = 32; o > 0; o >>= 1) v += shflxi(v, o, lane);
;   return v;
; }
; template <int NJ>
; DI void select_row(const float* row, int n, u64* bmrow, int lane) {
;     ...
;     unsigned cand = km & 0xff800000u;
; #pragma unroll 1
;     for (int pr = 0; pr < 4; ++pr) {
;       if (cand <= lo || cand >= hi) break;
;       int c = 0;
; #pragma unroll
;       for (int jj = 0; jj < NJ; ++jj)
;         asm volatile("v_cmp_le_u32 vcc, %1, %2\n\tv_addc_co_u32 %0, vcc, 0, %0, vcc" : "+v"(c) : "s"(cand), "v"(key[jj]) : "vcc");
;       c = wave_sum_i(c, lane);
;       if (c == 256) { T = cand; exact = true; break; }
;       if (c > 256) { lo = cand; break; }
;       hi = cand;
;       if (cand < 0x00800000u) break;
;       cand -= 0x00800000u;
;     }
.LBB0_721:
	v_cmp_gt_u32_e32 vcc, v115, v0
	v_cmp_lt_u32_e64 s[6:7], v115, v36
	s_and_b64 s[40:41], vcc, s[6:7]
	s_andn2_b64 s[6:7], s[26:27], exec
	s_and_b64 s[26:27], s[38:39], exec
	s_or_b64 s[26:27], s[6:7], s[26:27]
	s_or_b64 s[24:25], s[24:25], exec
	s_and_saveexec_b64 s[6:7], s[40:41]
	s_cbranch_execz .LBB0_720
	v_mov_b32_e32 v40, v1
	v_cmp_le_u32 vcc, v115, v79
	v_addc_co_u32 v40, vcc, 0, v40, vcc
	s_movk_i32 s40, 0x100
	v_cmp_le_u32 vcc, v115, v77
	v_addc_co_u32 v40, vcc, 0, v40, vcc
	s_mov_b64 s[44:45], -1
	v_cmp_le_u32 vcc, v115, v75
	v_addc_co_u32 v40, vcc, 0, v40, vcc
	s_mov_b64 s[42:43], -1
	v_cmp_le_u32 vcc, v115, v73
	v_addc_co_u32 v40, vcc, 0, v40, vcc
	s_nop 0
	v_cmp_le_u32 vcc, v115, v71
	v_addc_co_u32 v40, vcc, 0, v40, vcc
	s_nop 0
	v_cmp_le_u32 vcc, v115, v69
	v_addc_co_u32 v40, vcc, 0, v40, vcc
	s_nop 0
	v_cmp_le_u32 vcc, v115, v67
	v_addc_co_u32 v40, vcc, 0, v40, vcc
	s_nop 0
	v_cmp_le_u32 vcc, v115, v65
	v_addc_co_u32 v40, vcc, 0, v40, vcc
	s_nop 0
	v_cmp_le_u32 vcc, v115, v63
	v_addc_co_u32 v40, vcc, 0, v40, vcc
	s_nop 0
	v_cmp_le_u32 vcc, v115, v61
	v_addc_co_u32 v40, vcc, 0, v40, vcc
	s_nop 0
	v_cmp_le_u32 vcc, v115, v59
	v_addc_co_u32 v40, vcc, 0, v40, vcc
	s_nop 0
	v_cmp_le_u32 vcc, v115, v57
	v_addc_co_u32 v40, vcc, 0, v40, vcc
	s_nop 0
	v_cmp_le_u32 vcc, v115, v55
	v_addc_co_u32 v40, vcc, 0, v40, vcc
	s_nop 0
	v_cmp_le_u32 vcc, v115, v51
	v_addc_co_u32 v40, vcc, 0, v40, vcc
	s_nop 0
	v_cmp_le_u32 vcc, v115, v53
	v_addc_co_u32 v40, vcc, 0, v40, vcc
	s_nop 0
	v_cmp_le_u32 vcc, v115, v49
	v_addc_co_u32 v40, vcc, 0, v40, vcc
	s_nop 0
	v_cmp_le_u32 vcc, v115, v47
	v_addc_co_u32 v40, vcc, 0, v40, vcc
	s_nop 0
	v_cmp_le_u32 vcc, v115, v45
	v_addc_co_u32 v40, vcc, 0, v40, vcc
	s_nop 0
	v_cmp_le_u32 vcc, v115, v43
	v_addc_co_u32 v40, vcc, 0, v40, vcc
	s_nop 0
	v_cmp_le_u32 vcc, v115, v41
	v_addc_co_u32 v40, vcc, 0, v40, vcc
	s_nop 0
	v_cmp_le_u32 vcc, v115, v39
	v_addc_co_u32 v40, vcc, 0, v40, vcc
	s_nop 0
	v_cmp_le_u32 vcc, v115, v37
	v_addc_co_u32 v40, vcc, 0, v40, vcc
	s_nop 0
	v_cmp_le_u32 vcc, v115, v35
	v_addc_co_u32 v40, vcc, 0, v40, vcc
	s_nop 0
	v_cmp_le_u32 vcc, v115, v33
	v_addc_co_u32 v40, vcc, 0, v40, vcc
	s_nop 0
	v_cmp_le_u32 vcc, v115, v31
	v_addc_co_u32 v40, vcc, 0, v40, vcc
	s_nop 0
	v_cmp_le_u32 vcc, v115, v29
	v_addc_co_u32 v40, vcc, 0, v40, vcc
	s_nop 0
	v_cmp_le_u32 vcc, v115, v27
	v_addc_co_u32 v40, vcc, 0, v40, vcc
	s_nop 0
	v_cmp_le_u32 vcc, v115, v25
	v_addc_co_u32 v40, vcc, 0, v40, vcc
	s_nop 0
	v_cmp_le_u32 vcc, v115, v23
	v_addc_co_u32 v40, vcc, 0, v40, vcc
	s_nop 0
	v_cmp_le_u32 vcc, v115, v21
	v_addc_co_u32 v40, vcc, 0, v40, vcc
	s_nop 0
	v_cmp_le_u32 vcc, v115, v19
	v_addc_co_u32 v40, vcc, 0, v40, vcc
	s_nop 0
	v_cmp_le_u32 vcc, v115, v17
	v_addc_co_u32 v40, vcc, 0, v40, vcc
	s_nop 0
	v_cmp_le_u32 vcc, v115, v6
	v_addc_co_u32 v40, vcc, 0, v40, vcc
	s_nop 0
	v_cmp_le_u32 vcc, v115, v4
	v_addc_co_u32 v40, vcc, 0, v40, vcc
	s_nop 0
	v_cmp_le_u32 vcc, v115, v10
	v_addc_co_u32 v40, vcc, 0, v40, vcc
	s_nop 0
	v_cmp_le_u32 vcc, v115, v8
	v_addc_co_u32 v40, vcc, 0, v40, vcc
	s_nop 0
	v_cmp_le_u32 vcc, v115, v14
	v_addc_co_u32 v40, vcc, 0, v40, vcc
	s_nop 0
	v_cmp_le_u32 vcc, v115, v12
	v_addc_co_u32 v40, vcc, 0, v40, vcc
	s_nop 0
	v_cmp_le_u32 vcc, v115, v18
	v_addc_co_u32 v40, vcc, 0, v40, vcc
	s_nop 0
	v_cmp_le_u32 vcc, v115, v16
	v_addc_co_u32 v40, vcc, 0, v40, vcc
	s_nop 0
	v_cmp_le_u32 vcc, v115, v22
	v_addc_co_u32 v40, vcc, 0, v40, vcc
	s_nop 0
	v_cmp_le_u32 vcc, v115, v20
	v_addc_co_u32 v40, vcc, 0, v40, vcc
	s_nop 0
	v_cmp_le_u32 vcc, v115, v26
	v_addc_co_u32 v40, vcc, 0, v40, vcc
	s_nop 0
	v_cmp_le_u32 vcc, v115, v24
	v_addc_co_u32 v40, vcc, 0, v40, vcc
	s_nop 0
	v_cmp_le_u32 vcc, v115, v30
	v_addc_co_u32 v40, vcc, 0, v40, vcc
	s_nop 0
	v_cmp_le_u32 vcc, v115, v28
	v_addc_co_u32 v40, vcc, 0, v40, vcc
	s_nop 0
	v_cmp_le_u32 vcc, v115, v83
	v_addc_co_u32 v40, vcc, 0, v40, vcc
	s_nop 0
	v_cmp_le_u32 vcc, v115, v81
	v_addc_co_u32 v40, vcc, 0, v40, vcc
	s_nop 0
	v_cmp_le_u32 vcc, v115, v87
	v_addc_co_u32 v40, vcc, 0, v40, vcc
	s_nop 0
	v_cmp_le_u32 vcc, v115, v85
	v_addc_co_u32 v40, vcc, 0, v40, vcc
	s_nop 0
	v_cmp_le_u32 vcc, v115, v91
	v_addc_co_u32 v40, vcc, 0, v40, vcc
	s_nop 0
	v_cmp_le_u32 vcc, v115, v89
	v_addc_co_u32 v40, vcc, 0, v40, vcc
	s_nop 0
	v_cmp_le_u32 vcc, v115, v95
	v_addc_co_u32 v40, vcc, 0, v40, vcc
	s_nop 0
	v_cmp_le_u32 vcc, v115, v93
	v_addc_co_u32 v40, vcc, 0, v40, vcc
	s_nop 0
	v_cmp_le_u32 vcc, v115, v99
	v_addc_co_u32 v40, vcc, 0, v40, vcc
	s_nop 0
	v_cmp_le_u32 vcc, v115, v97
	v_addc_co_u32 v40, vcc, 0, v40, vcc
	s_nop 0
	v_cmp_le_u32 vcc, v115, v32
	v_addc_co_u32 v40, vcc, 0, v40, vcc
	s_nop 0
	v_cmp_le_u32 vcc, v115, v101
	v_addc_co_u32 v40, vcc, 0, v40, vcc
	s_nop 0
	v_cmp_le_u32 vcc, v115, v105
	v_addc_co_u32 v40, vcc, 0, v40, vcc
	s_nop 0
	v_cmp_le_u32 vcc, v115, v103
	v_addc_co_u32 v40, vcc, 0, v40, vcc
	s_nop 0
	v_cmp_le_u32 vcc, v115, v109
	v_addc_co_u32 v40, vcc, 0, v40, vcc
	s_nop 0
	v_cmp_le_u32 vcc, v115, v107
	v_addc_co_u32 v40, vcc, 0, v40, vcc
	s_nop 0
	v_cmp_le_u32 vcc, v115, v113
	v_addc_co_u32 v40, vcc, 0, v40, vcc
	s_nop 0
	v_cmp_le_u32 vcc, v115, v111
	v_addc_co_u32 v40, vcc, 0, v40, vcc
	s_nop 1
	v_add_u32_dpp v40, v40, v40 row_shr:1 row_mask:0xf bank_mask:0xf bound_ctrl:0
	s_nop 1
	v_add_u32_dpp v40, v40, v40 row_shr:2 row_mask:0xf bank_mask:0xf bound_ctrl:0
	s_nop 1
	v_add_u32_dpp v40, v40, v40 row_shr:4 row_mask:0xf bank_mask:0xf bound_ctrl:0
	s_nop 1
	v_add_u32_dpp v40, v40, v40 row_shr:8 row_mask:0xf bank_mask:0xf bound_ctrl:0
	s_nop 1
	v_add_u32_dpp v40, v40, v40 row_bcast:15 row_mask:0xa bank_mask:0xf
	s_nop 1
	v_add_u32_dpp v40, v40, v40 row_bcast:31 row_mask:0xc bank_mask:0xf
	s_nop 1
	v_readlane_b32 s98, v40, 63
	s_nop 1
	v_mov_b32_e32 v119, s98
	v_mov_b32_e32 v40, s98
	v_cmp_ne_u32_e32 vcc, s40, v119
	v_mov_b32_e32 v117, v115
	s_and_saveexec_b64 s[40:41], vcc
	s_cbranch_execz .LBB0_719
	s_movk_i32 s42, 0x101
	v_cmp_gt_i32_e32 vcc, s42, v119
	v_mov_b32_e32 v117, v115
	s_and_saveexec_b64 s[42:43], vcc
	s_cbranch_execz .LBB0_718
	v_subrev_co_u32_e32 v36, vcc, 0x800000, v115
	s_orn2_b64 s[44:45], vcc, exec
	s_nop 0
	v_cndmask_b32_e32 v117, v36, v115, vcc
	v_mov_b32_e32 v36, v115
	v_mov_b32_e32 v115, v0
	s_branch .LBB0_718

; DI int shflxi(int v, int m, int lane) { return __builtin_amdgcn_ds_bpermute((lane ^ m) << 2, v); }
; DI int wave_sum_i(int v, int lane) {
; #pragma unroll
;   for (int o = 32; o > 0; o >>= 1) v += shflxi(v, o, lane);
;   return v;
; }
; template <int NJ>
; DI void select_row(const float* row, int n, u64* bmrow, int lane) {
;     ...
;     unsigned cand = km & 0xff800000u;
; #pragma unroll 1
;     for (int pr = 0; pr < 4; ++pr) {
;       if (cand <= lo || cand >= hi) break;
;       int c = 0;
; #pragma unroll
;       for (int jj = 0; jj < NJ; ++jj)
;         asm volatile("v_cmp_le_u32 vcc, %1, %2\n\tv_addc_co_u32 %0, vcc, 0, %0, vcc" : "+v"(c) : "s"(cand), "v"(key[jj]) : "vcc");
;       c = wave_sum_i(c, lane);
;       if (c == 256) { T = cand; exact = true; break; }
;       if (c > 256) { lo = cand; break; }
;       hi = cand;
;       if (cand < 0x00800000u) break;
;       cand -= 0x00800000u;
;     }
.LBB0_787:
	v_cmp_gt_u32_e32 vcc, v51, v45
	v_cmp_lt_u32_e64 s[6:7], v51, v38
	s_and_b64 s[38:39], vcc, s[6:7]
	s_andn2_b64 s[6:7], s[24:25], exec
	s_and_b64 s[24:25], s[26:27], exec
	s_or_b64 s[24:25], s[6:7], s[24:25]
	s_or_b64 s[22:23], s[22:23], exec
	s_and_saveexec_b64 s[6:7], s[38:39]
	s_cbranch_execz .LBB0_786
	v_mov_b32_e32 v40, v1
	v_cmp_le_u32 vcc, v51, v43
	v_addc_co_u32 v40, vcc, 0, v40, vcc
	s_movk_i32 s38, 0x100
	v_cmp_le_u32 vcc, v51, v41
	v_addc_co_u32 v40, vcc, 0, v40, vcc
	s_mov_b64 s[42:43], -1
	v_cmp_le_u32 vcc, v51, v39
	v_addc_co_u32 v40, vcc, 0, v40, vcc
	s_mov_b64 s[40:41], -1
	v_cmp_le_u32 vcc, v51, v0
	v_addc_co_u32 v40, vcc, 0, v40, vcc
	s_nop 0
	v_cmp_le_u32 vcc, v51, v6
	v_addc_co_u32 v40, vcc, 0, v40, vcc
	s_nop 0
	v_cmp_le_u32 vcc, v51, v4
	v_addc_co_u32 v40, vcc, 0, v40, vcc
	s_nop 0
	v_cmp_le_u32 vcc, v51, v10
	v_addc_co_u32 v40, vcc, 0, v40, vcc
	s_nop 0
	v_cmp_le_u32 vcc, v51, v8
	v_addc_co_u32 v40, vcc, 0, v40, vcc
	s_nop 0
	v_cmp_le_u32 vcc, v51, v14
	v_addc_co_u32 v40, vcc, 0, v40, vcc
	s_nop 0
	v_cmp_le_u32 vcc, v51, v12
	v_addc_co_u32 v40, vcc, 0, v40, vcc
	s_nop 0
	v_cmp_le_u32 vcc, v51, v17
	v_addc_co_u32 v40, vcc, 0, v40, vcc
	s_nop 0
	v_cmp_le_u32 vcc, v51, v16
	v_addc_co_u32 v40, vcc, 0, v40, vcc
	s_nop 0
	v_cmp_le_u32 vcc, v51, v19
	v_addc_co_u32 v40, vcc, 0, v40, vcc
	s_nop 0
	v_cmp_le_u32 vcc, v51, v18
	v_addc_co_u32 v40, vcc, 0, v40, vcc
	s_nop 0
	v_cmp_le_u32 vcc, v51, v21
	v_addc_co_u32 v40, vcc, 0, v40, vcc
	s_nop 0
	v_cmp_le_u32 vcc, v51, v20
	v_addc_co_u32 v40, vcc, 0, v40, vcc
	s_nop 0
	v_cmp_le_u32 vcc, v51, v23
	v_addc_co_u32 v40, vcc, 0, v40, vcc
	s_nop 0
	v_cmp_le_u32 vcc, v51, v22
	v_addc_co_u32 v40, vcc, 0, v40, vcc
	s_nop 0
	v_cmp_le_u32 vcc, v51, v25
	v_addc_co_u32 v40, vcc, 0, v40, vcc
	s_nop 0
	v_cmp_le_u32 vcc, v51, v24
	v_addc_co_u32 v40, vcc, 0, v40, vcc
	s_nop 0
	v_cmp_le_u32 vcc, v51, v27
	v_addc_co_u32 v40, vcc, 0, v40, vcc
	s_nop 0
	v_cmp_le_u32 vcc, v51, v26
	v_addc_co_u32 v40, vcc, 0, v40, vcc
	s_nop 0
	v_cmp_le_u32 vcc, v51, v29
	v_addc_co_u32 v40, vcc, 0, v40, vcc
	s_nop 0
	v_cmp_le_u32 vcc, v51, v28
	v_addc_co_u32 v40, vcc, 0, v40, vcc
	s_nop 0
	v_cmp_le_u32 vcc, v51, v31
	v_addc_co_u32 v40, vcc, 0, v40, vcc
	s_nop 0
	v_cmp_le_u32 vcc, v51, v30
	v_addc_co_u32 v40, vcc, 0, v40, vcc
	s_nop 0
	v_cmp_le_u32 vcc, v51, v33
	v_addc_co_u32 v40, vcc, 0, v40, vcc
	s_nop 0
	v_cmp_le_u32 vcc, v51, v32
	v_addc_co_u32 v40, vcc, 0, v40, vcc
	s_nop 0
	v_cmp_le_u32 vcc, v51, v35
	v_addc_co_u32 v40, vcc, 0, v40, vcc
	s_nop 0
	v_cmp_le_u32 vcc, v51, v34
	v_addc_co_u32 v40, vcc, 0, v40, vcc
	s_nop 0
	v_cmp_le_u32 vcc, v51, v37
	v_addc_co_u32 v40, vcc, 0, v40, vcc
	s_nop 0
	v_cmp_le_u32 vcc, v51, v36
	v_addc_co_u32 v40, vcc, 0, v40, vcc
	s_nop 1
	v_add_u32_dpp v40, v40, v40 row_shr:1 row_mask:0xf bank_mask:0xf bound_ctrl:0
	s_nop 1
	v_add_u32_dpp v40, v40, v40 row_shr:2 row_mask:0xf bank_mask:0xf bound_ctrl:0
	s_nop 1
	v_add_u32_dpp v40, v40, v40 row_shr:4 row_mask:0xf bank_mask:0xf bound_ctrl:0
	s_nop 1
	v_add_u32_dpp v40, v40, v40 row_shr:8 row_mask:0xf bank_mask:0xf bound_ctrl:0
	s_nop 1
	v_add_u32_dpp v40, v40, v40 row_bcast:15 row_mask:0xa bank_mask:0xf
	s_nop 1
	v_add_u32_dpp v40, v40, v40 row_bcast:31 row_mask:0xc bank_mask:0xf
	s_nop 1
	v_readlane_b32 s98, v40, 63
	s_nop 1
	v_mov_b32_e32 v55, s98
	v_mov_b32_e32 v40, s98
	v_cmp_ne_u32_e32 vcc, s38, v55
	v_mov_b32_e32 v53, v51
	s_and_saveexec_b64 s[38:39], vcc
	s_cbranch_execz .LBB0_785
	s_movk_i32 s40, 0x101
	v_cmp_gt_i32_e32 vcc, s40, v55
	v_mov_b32_e32 v53, v51
	s_and_saveexec_b64 s[40:41], vcc
	s_cbranch_execz .LBB0_784
	v_subrev_co_u32_e32 v38, vcc, 0x800000, v51
	s_orn2_b64 s[42:43], vcc, exec
	s_nop 0
	v_cndmask_b32_e32 v53, v38, v51, vcc
	v_mov_b32_e32 v38, v51
	v_mov_b32_e32 v51, v45
	s_branch .LBB0_784

; DI int shflxi(int v, int m, int lane) { return __builtin_amdgcn_ds_bpermute((lane ^ m) << 2, v); }
; DI int wave_sum_i(int v, int lane) {
; #pragma unroll
;   for (int o = 32; o > 0; o >>= 1) v += shflxi(v, o, lane);
;   return v;
; }
; template <int NJ>
; DI void select_row(const float* row, int n, u64* bmrow, int lane) {
;     ...
;   while (!exact && hi - lo > 1u) {
;     const unsigned cand = lo + ((hi - lo) >> 1);
;     int c = 0;
; #pragma unroll
;     for (int jj = 0; jj < NJ; ++jj)
;       asm volatile("v_cmp_le_u32 vcc, %1, %2\n\tv_addc_co_u32 %0, vcc, 0, %0, vcc" : "+v"(c) : "s"(cand), "v"(key[jj]) : "vcc");
;     c = wave_sum_i(c, lane);
;     if (c == 256) { T = cand; exact = true; }
;     else if (c > 256) lo = cand; else hi = cand;
;   }
.LBB0_793:
	v_lshrrev_b32_e32 v40, 1, v49
	v_mov_b32_e32 v49, v1
	v_add_u32_e32 v40, v45, v40
	v_cmp_le_u32 vcc, v40, v43
	v_addc_co_u32 v49, vcc, 0, v49, vcc
	s_nop 0
	v_cmp_le_u32 vcc, v40, v41
	v_addc_co_u32 v49, vcc, 0, v49, vcc
	s_nop 0
	v_cmp_le_u32 vcc, v40, v39
	v_addc_co_u32 v49, vcc, 0, v49, vcc
	s_nop 0
	v_cmp_le_u32 vcc, v40, v0
	v_addc_co_u32 v49, vcc, 0, v49, vcc
	s_nop 0
	v_cmp_le_u32 vcc, v40, v6
	v_addc_co_u32 v49, vcc, 0, v49, vcc
	s_nop 0
	v_cmp_le_u32 vcc, v40, v4
	v_addc_co_u32 v49, vcc, 0, v49, vcc
	s_nop 0
	v_cmp_le_u32 vcc, v40, v10
	v_addc_co_u32 v49, vcc, 0, v49, vcc
	s_nop 0
	v_cmp_le_u32 vcc, v40, v8
	v_addc_co_u32 v49, vcc, 0, v49, vcc
	s_nop 0
	v_cmp_le_u32 vcc, v40, v14
	v_addc_co_u32 v49, vcc, 0, v49, vcc
	s_nop 0
	v_cmp_le_u32 vcc, v40, v12
	v_addc_co_u32 v49, vcc, 0, v49, vcc
	s_nop 0
	v_cmp_le_u32 vcc, v40, v17
	v_addc_co_u32 v49, vcc, 0, v49, vcc
	s_nop 0
	v_cmp_le_u32 vcc, v40, v16
	v_addc_co_u32 v49, vcc, 0, v49, vcc
	s_nop 0
	v_cmp_le_u32 vcc, v40, v19
	v_addc_co_u32 v49, vcc, 0, v49, vcc
	s_nop 0
	v_cmp_le_u32 vcc, v40, v18
	v_addc_co_u32 v49, vcc, 0, v49, vcc
	s_nop 0
	v_cmp_le_u32 vcc, v40, v21
	v_addc_co_u32 v49, vcc, 0, v49, vcc
	s_nop 0
	v_cmp_le_u32 vcc, v40, v20
	v_addc_co_u32 v49, vcc, 0, v49, vcc
	s_nop 0
	v_cmp_le_u32 vcc, v40, v23
	v_addc_co_u32 v49, vcc, 0, v49, vcc
	s_nop 0
	v_cmp_le_u32 vcc, v40, v22
	v_addc_co_u32 v49, vcc, 0, v49, vcc
	s_nop 0
	v_cmp_le_u32 vcc, v40, v25
	v_addc_co_u32 v49, vcc, 0, v49, vcc
	s_nop 0
	v_cmp_le_u32 vcc, v40, v24
	v_addc_co_u32 v49, vcc, 0, v49, vcc
	s_nop 0
	v_cmp_le_u32 vcc, v40, v27
	v_addc_co_u32 v49, vcc, 0, v49, vcc
	s_nop 0
	v_cmp_le_u32 vcc, v40, v26
	v_addc_co_u32 v49, vcc, 0, v49, vcc
	s_nop 0
	v_cmp_le_u32 vcc, v40, v29
	v_addc_co_u32 v49, vcc, 0, v49, vcc
	s_nop 0
	v_cmp_le_u32 vcc, v40, v28
	v_addc_co_u32 v49, vcc, 0, v49, vcc
	s_nop 0
	v_cmp_le_u32 vcc, v40, v31
	v_addc_co_u32 v49, vcc, 0, v49, vcc
	s_nop 0
	v_cmp_le_u32 vcc, v40, v30
	v_addc_co_u32 v49, vcc, 0, v49, vcc
	s_nop 0
	v_cmp_le_u32 vcc, v40, v33
	v_addc_co_u32 v49, vcc, 0, v49, vcc
	s_nop 0
	v_cmp_le_u32 vcc, v40, v32
	v_addc_co_u32 v49, vcc, 0, v49, vcc
	s_nop 0
	v_cmp_le_u32 vcc, v40, v35
	v_addc_co_u32 v49, vcc, 0, v49, vcc
	s_nop 0
	v_cmp_le_u32 vcc, v40, v34
	v_addc_co_u32 v49, vcc, 0, v49, vcc
	s_nop 0
	v_cmp_le_u32 vcc, v40, v37
	v_addc_co_u32 v49, vcc, 0, v49, vcc
	s_nop 0
	v_cmp_le_u32 vcc, v40, v36
	v_addc_co_u32 v49, vcc, 0, v49, vcc
	s_nop 1
	v_add_u32_dpp v49, v49, v49 row_shr:1 row_mask:0xf bank_mask:0xf bound_ctrl:0
	s_nop 1
	v_add_u32_dpp v49, v49, v49 row_shr:2 row_mask:0xf bank_mask:0xf bound_ctrl:0
	s_nop 1
	v_add_u32_dpp v49, v49, v49 row_shr:4 row_mask:0xf bank_mask:0xf bound_ctrl:0
	s_nop 1
	v_add_u32_dpp v49, v49, v49 row_shr:8 row_mask:0xf bank_mask:0xf bound_ctrl:0
	s_nop 1
	v_add_u32_dpp v49, v49, v49 row_bcast:15 row_mask:0xa bank_mask:0xf
	s_nop 1
	v_add_u32_dpp v49, v49, v49 row_bcast:31 row_mask:0xc bank_mask:0xf
	s_nop 1
	v_readlane_b32 s98, v49, 63
	s_nop 1
	v_mov_b32_e32 v49, s98
	v_cmp_lt_i32_e32 vcc, s26, v49
	s_nop 1
	v_cndmask_b32_e32 v51, v45, v40, vcc
	v_cmp_lt_i32_e32 vcc, s27, v49
	s_nop 1
	v_cndmask_b32_e32 v38, v40, v38, vcc
	v_cmp_eq_u32_e32 vcc, s26, v49
	s_nop 1
	v_cndmask_b32_e32 v45, v51, v45, vcc
	v_sub_u32_e32 v49, v38, v45
	v_cmp_gt_u32_e64 s[6:7], 2, v49
	s_or_b64 s[6:7], vcc, s[6:7]
	s_and_b64 s[6:7], exec, s[6:7]
	s_or_b64 s[22:23], s[6:7], s[22:23]
	s_andn2_b64 s[6:7], s[24:25], exec
	s_and_b64 s[24:25], vcc, exec
	v_cndmask_b32_e32 v47, v47, v40, vcc
	s_or_b64 s[24:25], s[6:7], s[24:25]
	s_andn2_b64 exec, exec, s[22:23]
	s_cbranch_execnz .LBB0_793
	s_or_b64 exec, exec, s[22:23]
	s_andn2_b64 s[6:7], s[18:19], exec
	s_and_b64 s[18:19], s[24:25], exec
	s_or_b64 s[18:19], s[6:7], s[18:19]

; DI int shflxi(int v, int m, int lane) { return __builtin_amdgcn_ds_bpermute((lane ^ m) << 2, v); }
; DI int wave_sum_i(int v, int lane) {
; #pragma unroll
;   for (int o = 32; o > 0; o >>= 1) v += shflxi(v, o, lane);
;   return v;
; }
; template <int NJ>
; DI void select_row(const float* row, int n, u64* bmrow, int lane) {
;     ...
;         const unsigned cand = X | (1u << bit);
;         int c = 0;
; #pragma unroll
;         for (int jj = 0; jj < NJ; ++jj) {
;           unsigned tmp;
;           asm volatile("v_add_u32 %1, %7, %5\n\tv_cmp_eq_u32 vcc, %2, %3\n\tv_cndmask_b32 %1, %4, %1, vcc\n\tv_cmp_gt_u32 vcc, %6, %1\n\tv_addc_co_u32 %0, vcc, 0, %0, vcc"
;                        : "+v"(c), "=&v"(tmp) : "s"(T), "v"(key[jj]), "v"(bigv), "v"(lane), "s"(cand), "n"(jj * 64) : "vcc");
;         }
;         c = wave_sum_i(c, lane);
;         if (c <= need) X = cand;
;       }
.LBB0_798:
	v_mov_b32_e32 v51, v1
	v_lshl_or_b32 v40, 1, s20, v38
	v_add_u32 v53, 0, v2
	v_cmp_eq_u32 vcc, v45, v43
	v_cndmask_b32 v53, v49, v53, vcc
	v_cmp_gt_u32 vcc, v40, v53
	v_addc_co_u32 v51, vcc, 0, v51, vcc
	s_add_i32 s20, s20, -1
	v_add_u32 v53, 64, v2
	v_cmp_eq_u32 vcc, v45, v41
	v_cndmask_b32 v53, v49, v53, vcc
	v_cmp_gt_u32 vcc, v40, v53
	v_addc_co_u32 v51, vcc, 0, v51, vcc
	s_cmp_lg_u32 s20, -1
	v_add_u32 v53, 0x80, v2
	v_cmp_eq_u32 vcc, v45, v39
	v_cndmask_b32 v53, v49, v53, vcc
	v_cmp_gt_u32 vcc, v40, v53
	v_addc_co_u32 v51, vcc, 0, v51, vcc
	s_nop 0
	v_add_u32 v53, 0xc0, v2
	v_cmp_eq_u32 vcc, v45, v0
	v_cndmask_b32 v53, v49, v53, vcc
	v_cmp_gt_u32 vcc, v40, v53
	v_addc_co_u32 v51, vcc, 0, v51, vcc
	s_nop 0
	v_add_u32 v53, 0x100, v2
	v_cmp_eq_u32 vcc, v45, v6
	v_cndmask_b32 v53, v49, v53, vcc
	v_cmp_gt_u32 vcc, v40, v53
	v_addc_co_u32 v51, vcc, 0, v51, vcc
	s_nop 0
	v_add_u32 v53, 0x140, v2
	v_cmp_eq_u32 vcc, v45, v4
	v_cndmask_b32 v53, v49, v53, vcc
	v_cmp_gt_u32 vcc, v40, v53
	v_addc_co_u32 v51, vcc, 0, v51, vcc
	s_nop 0
	v_add_u32 v53, 0x180, v2
	v_cmp_eq_u32 vcc, v45, v10
	v_cndmask_b32 v53, v49, v53, vcc
	v_cmp_gt_u32 vcc, v40, v53
	v_addc_co_u32 v51, vcc, 0, v51, vcc
	s_nop 0
	v_add_u32 v53, 0x1c0, v2
	v_cmp_eq_u32 vcc, v45, v8
	v_cndmask_b32 v53, v49, v53, vcc
	v_cmp_gt_u32 vcc, v40, v53
	v_addc_co_u32 v51, vcc, 0, v51, vcc
	s_nop 0
	v_add_u32 v53, 0x200, v2
	v_cmp_eq_u32 vcc, v45, v14
	v_cndmask_b32 v53, v49, v53, vcc
	v_cmp_gt_u32 vcc, v40, v53
	v_addc_co_u32 v51, vcc, 0, v51, vcc
	s_nop 0
	v_add_u32 v53, 0x240, v2
	v_cmp_eq_u32 vcc, v45, v12
	v_cndmask_b32 v53, v49, v53, vcc
	v_cmp_gt_u32 vcc, v40, v53
	v_addc_co_u32 v51, vcc, 0, v51, vcc
	s_nop 0
	v_add_u32 v53, 0x280, v2
	v_cmp_eq_u32 vcc, v45, v17
	v_cndmask_b32 v53, v49, v53, vcc
	v_cmp_gt_u32 vcc, v40, v53
	v_addc_co_u32 v51, vcc, 0, v51, vcc
	s_nop 0
	v_add_u32 v53, 0x2c0, v2
	v_cmp_eq_u32 vcc, v45, v16
	v_cndmask_b32 v53, v49, v53, vcc
	v_cmp_gt_u32 vcc, v40, v53
	v_addc_co_u32 v51, vcc, 0, v51, vcc
	s_nop 0
	v_add_u32 v53, 0x300, v2
	v_cmp_eq_u32 vcc, v45, v19
	v_cndmask_b32 v53, v49, v53, vcc
	v_cmp_gt_u32 vcc, v40, v53
	v_addc_co_u32 v51, vcc, 0, v51, vcc
	s_nop 0
	v_add_u32 v53, 0x340, v2
	v_cmp_eq_u32 vcc, v45, v18
	v_cndmask_b32 v53, v49, v53, vcc
	v_cmp_gt_u32 vcc, v40, v53
	v_addc_co_u32 v51, vcc, 0, v51, vcc
	s_nop 0
	v_add_u32 v53, 0x380, v2
	v_cmp_eq_u32 vcc, v45, v21
	v_cndmask_b32 v53, v49, v53, vcc
	v_cmp_gt_u32 vcc, v40, v53
	v_addc_co_u32 v51, vcc, 0, v51, vcc
	s_nop 0
	v_add_u32 v53, 0x3c0, v2
	v_cmp_eq_u32 vcc, v45, v20
	v_cndmask_b32 v53, v49, v53, vcc
	v_cmp_gt_u32 vcc, v40, v53
	v_addc_co_u32 v51, vcc, 0, v51, vcc
	s_nop 0
	v_add_u32 v53, 0x400, v2
	v_cmp_eq_u32 vcc, v45, v23
	v_cndmask_b32 v53, v49, v53, vcc
	v_cmp_gt_u32 vcc, v40, v53
	v_addc_co_u32 v51, vcc, 0, v51, vcc
	s_nop 0
	v_add_u32 v53, 0x440, v2
	v_cmp_eq_u32 vcc, v45, v22
	v_cndmask_b32 v53, v49, v53, vcc
	v_cmp_gt_u32 vcc, v40, v53
	v_addc_co_u32 v51, vcc, 0, v51, vcc
	s_nop 0
	v_add_u32 v53, 0x480, v2
	v_cmp_eq_u32 vcc, v45, v25
	v_cndmask_b32 v53, v49, v53, vcc
	v_cmp_gt_u32 vcc, v40, v53
	v_addc_co_u32 v51, vcc, 0, v51, vcc
	s_nop 0
	v_add_u32 v53, 0x4c0, v2
	v_cmp_eq_u32 vcc, v45, v24
	v_cndmask_b32 v53, v49, v53, vcc
	v_cmp_gt_u32 vcc, v40, v53
	v_addc_co_u32 v51, vcc, 0, v51, vcc
	s_nop 0
	v_add_u32 v53, 0x500, v2
	v_cmp_eq_u32 vcc, v45, v27
	v_cndmask_b32 v53, v49, v53, vcc
	v_cmp_gt_u32 vcc, v40, v53
	v_addc_co_u32 v51, vcc, 0, v51, vcc
	s_nop 0
	v_add_u32 v53, 0x540, v2
	v_cmp_eq_u32 vcc, v45, v26
	v_cndmask_b32 v53, v49, v53, vcc
	v_cmp_gt_u32 vcc, v40, v53
	v_addc_co_u32 v51, vcc, 0, v51, vcc
	s_nop 0
	v_add_u32 v53, 0x580, v2
	v_cmp_eq_u32 vcc, v45, v29
	v_cndmask_b32 v53, v49, v53, vcc
	v_cmp_gt_u32 vcc, v40, v53
	v_addc_co_u32 v51, vcc, 0, v51, vcc
	s_nop 0
	v_add_u32 v53, 0x5c0, v2
	v_cmp_eq_u32 vcc, v45, v28
	v_cndmask_b32 v53, v49, v53, vcc
	v_cmp_gt_u32 vcc, v40, v53
	v_addc_co_u32 v51, vcc, 0, v51, vcc
	s_nop 0
	v_add_u32 v53, 0x600, v2
	v_cmp_eq_u32 vcc, v45, v31
	v_cndmask_b32 v53, v49, v53, vcc
	v_cmp_gt_u32 vcc, v40, v53
	v_addc_co_u32 v51, vcc, 0, v51, vcc
	s_nop 0
	v_add_u32 v53, 0x640, v2
	v_cmp_eq_u32 vcc, v45, v30
	v_cndmask_b32 v53, v49, v53, vcc
	v_cmp_gt_u32 vcc, v40, v53
	v_addc_co_u32 v51, vcc, 0, v51, vcc
	s_nop 0
	v_add_u32 v53, 0x680, v2
	v_cmp_eq_u32 vcc, v45, v33
	v_cndmask_b32 v53, v49, v53, vcc
	v_cmp_gt_u32 vcc, v40, v53
	v_addc_co_u32 v51, vcc, 0, v51, vcc
	s_nop 0
	v_add_u32 v53, 0x6c0, v2
	v_cmp_eq_u32 vcc, v45, v32
	v_cndmask_b32 v53, v49, v53, vcc
	v_cmp_gt_u32 vcc, v40, v53
	v_addc_co_u32 v51, vcc, 0, v51, vcc
	s_nop 0
	v_add_u32 v53, 0x700, v2
	v_cmp_eq_u32 vcc, v45, v35
	v_cndmask_b32 v53, v49, v53, vcc
	v_cmp_gt_u32 vcc, v40, v53
	v_addc_co_u32 v51, vcc, 0, v51, vcc
	s_nop 0
	v_add_u32 v53, 0x740, v2
	v_cmp_eq_u32 vcc, v45, v34
	v_cndmask_b32 v53, v49, v53, vcc
	v_cmp_gt_u32 vcc, v40, v53
	v_addc_co_u32 v51, vcc, 0, v51, vcc
	s_nop 0
	v_add_u32 v53, 0x780, v2
	v_cmp_eq_u32 vcc, v45, v37
	v_cndmask_b32 v53, v49, v53, vcc
	v_cmp_gt_u32 vcc, v40, v53
	v_addc_co_u32 v51, vcc, 0, v51, vcc
	s_nop 0
	v_add_u32 v53, 0x7c0, v2
	v_cmp_eq_u32 vcc, v45, v36
	v_cndmask_b32 v53, v49, v53, vcc
	v_cmp_gt_u32 vcc, v40, v53
	v_addc_co_u32 v51, vcc, 0, v51, vcc
	s_nop 1
	v_add_u32_dpp v51, v51, v51 row_shr:1 row_mask:0xf bank_mask:0xf bound_ctrl:0
	s_nop 1
	v_add_u32_dpp v51, v51, v51 row_shr:2 row_mask:0xf bank_mask:0xf bound_ctrl:0
	s_nop 1
	v_add_u32_dpp v51, v51, v51 row_shr:4 row_mask:0xf bank_mask:0xf bound_ctrl:0
	s_nop 1
	v_add_u32_dpp v51, v51, v51 row_shr:8 row_mask:0xf bank_mask:0xf bound_ctrl:0
	s_nop 1
	v_add_u32_dpp v51, v51, v51 row_bcast:15 row_mask:0xa bank_mask:0xf
	s_nop 1
	v_add_u32_dpp v51, v51, v51 row_bcast:31 row_mask:0xc bank_mask:0xf
	s_nop 1
	v_readlane_b32 s98, v51, 63
	s_nop 1
	v_mov_b32_e32 v51, s98
	v_cmp_gt_i32_e32 vcc, v51, v47
	s_nop 1
	v_cndmask_b32_e32 v38, v40, v38, vcc
	s_cbranch_scc1 .LBB0_798

; DI int shflxi(int v, int m, int lane) { return __builtin_amdgcn_ds_bpermute((lane ^ m) << 2, v); }
; DI int wave_sum_i(int v, int lane) {
; #pragma unroll
;   for (int o = 32; o > 0; o >>= 1) v += shflxi(v, o, lane);
;   return v;
; }
; template <int NJ>
; DI void select_row(const float* row, int n, u64* bmrow, int lane) {
;     ...
;   while (!exact && hi - lo > 1u) {
;     const unsigned cand = lo + ((hi - lo) >> 1);
;     int c = 0;
; #pragma unroll
;     for (int jj = 0; jj < NJ; ++jj)
;       asm volatile("v_cmp_le_u32 vcc, %1, %2\n\tv_addc_co_u32 %0, vcc, 0, %0, vcc" : "+v"(c) : "s"(cand), "v"(key[jj]) : "vcc");
;     c = wave_sum_i(c, lane);
;     if (c == 256) { T = cand; exact = true; }
;     else if (c > 256) lo = cand; else hi = cand;
;   }
.LBB0_806:
	v_lshrrev_b32_e32 v38, 1, v38
	v_mov_b32_e32 v40, v1
	v_add_u32_e32 v38, v0, v38
	v_cmp_le_u32 vcc, v38, v79
	v_addc_co_u32 v40, vcc, 0, v40, vcc
	s_nop 0
	v_cmp_le_u32 vcc, v38, v77
	v_addc_co_u32 v40, vcc, 0, v40, vcc
	s_nop 0
	v_cmp_le_u32 vcc, v38, v75
	v_addc_co_u32 v40, vcc, 0, v40, vcc
	s_nop 0
	v_cmp_le_u32 vcc, v38, v73
	v_addc_co_u32 v40, vcc, 0, v40, vcc
	s_nop 0
	v_cmp_le_u32 vcc, v38, v71
	v_addc_co_u32 v40, vcc, 0, v40, vcc
	s_nop 0
	v_cmp_le_u32 vcc, v38, v69
	v_addc_co_u32 v40, vcc, 0, v40, vcc
	s_nop 0
	v_cmp_le_u32 vcc, v38, v67
	v_addc_co_u32 v40, vcc, 0, v40, vcc
	s_nop 0
	v_cmp_le_u32 vcc, v38, v65
	v_addc_co_u32 v40, vcc, 0, v40, vcc
	s_nop 0
	v_cmp_le_u32 vcc, v38, v63
	v_addc_co_u32 v40, vcc, 0, v40, vcc
	s_nop 0
	v_cmp_le_u32 vcc, v38, v61
	v_addc_co_u32 v40, vcc, 0, v40, vcc
	s_nop 0
	v_cmp_le_u32 vcc, v38, v59
	v_addc_co_u32 v40, vcc, 0, v40, vcc
	s_nop 0
	v_cmp_le_u32 vcc, v38, v57
	v_addc_co_u32 v40, vcc, 0, v40, vcc
	s_nop 0
	v_cmp_le_u32 vcc, v38, v55
	v_addc_co_u32 v40, vcc, 0, v40, vcc
	s_nop 0
	v_cmp_le_u32 vcc, v38, v51
	v_addc_co_u32 v40, vcc, 0, v40, vcc
	s_nop 0
	v_cmp_le_u32 vcc, v38, v53
	v_addc_co_u32 v40, vcc, 0, v40, vcc
	s_nop 0
	v_cmp_le_u32 vcc, v38, v49
	v_addc_co_u32 v40, vcc, 0, v40, vcc
	s_nop 0
	v_cmp_le_u32 vcc, v38, v47
	v_addc_co_u32 v40, vcc, 0, v40, vcc
	s_nop 0
	v_cmp_le_u32 vcc, v38, v45
	v_addc_co_u32 v40, vcc, 0, v40, vcc
	s_nop 0
	v_cmp_le_u32 vcc, v38, v43
	v_addc_co_u32 v40, vcc, 0, v40, vcc
	s_nop 0
	v_cmp_le_u32 vcc, v38, v41
	v_addc_co_u32 v40, vcc, 0, v40, vcc
	s_nop 0
	v_cmp_le_u32 vcc, v38, v39
	v_addc_co_u32 v40, vcc, 0, v40, vcc
	s_nop 0
	v_cmp_le_u32 vcc, v38, v37
	v_addc_co_u32 v40, vcc, 0, v40, vcc
	s_nop 0
	v_cmp_le_u32 vcc, v38, v35
	v_addc_co_u32 v40, vcc, 0, v40, vcc
	s_nop 0
	v_cmp_le_u32 vcc, v38, v33
	v_addc_co_u32 v40, vcc, 0, v40, vcc
	s_nop 0
	v_cmp_le_u32 vcc, v38, v31
	v_addc_co_u32 v40, vcc, 0, v40, vcc
	s_nop 0
	v_cmp_le_u32 vcc, v38, v29
	v_addc_co_u32 v40, vcc, 0, v40, vcc
	s_nop 0
	v_cmp_le_u32 vcc, v38, v27
	v_addc_co_u32 v40, vcc, 0, v40, vcc
	s_nop 0
	v_cmp_le_u32 vcc, v38, v25
	v_addc_co_u32 v40, vcc, 0, v40, vcc
	s_nop 0
	v_cmp_le_u32 vcc, v38, v23
	v_addc_co_u32 v40, vcc, 0, v40, vcc
	s_nop 0
	v_cmp_le_u32 vcc, v38, v21
	v_addc_co_u32 v40, vcc, 0, v40, vcc
	s_nop 0
	v_cmp_le_u32 vcc, v38, v19
	v_addc_co_u32 v40, vcc, 0, v40, vcc
	s_nop 0
	v_cmp_le_u32 vcc, v38, v17
	v_addc_co_u32 v40, vcc, 0, v40, vcc
	s_nop 0
	v_cmp_le_u32 vcc, v38, v6
	v_addc_co_u32 v40, vcc, 0, v40, vcc
	s_nop 0
	v_cmp_le_u32 vcc, v38, v4
	v_addc_co_u32 v40, vcc, 0, v40, vcc
	s_nop 0
	v_cmp_le_u32 vcc, v38, v10
	v_addc_co_u32 v40, vcc, 0, v40, vcc
	s_nop 0
	v_cmp_le_u32 vcc, v38, v8
	v_addc_co_u32 v40, vcc, 0, v40, vcc
	s_nop 0
	v_cmp_le_u32 vcc, v38, v14
	v_addc_co_u32 v40, vcc, 0, v40, vcc
	s_nop 0
	v_cmp_le_u32 vcc, v38, v12
	v_addc_co_u32 v40, vcc, 0, v40, vcc
	s_nop 0
	v_cmp_le_u32 vcc, v38, v18
	v_addc_co_u32 v40, vcc, 0, v40, vcc
	s_nop 0
	v_cmp_le_u32 vcc, v38, v16
	v_addc_co_u32 v40, vcc, 0, v40, vcc
	s_nop 0
	v_cmp_le_u32 vcc, v38, v22
	v_addc_co_u32 v40, vcc, 0, v40, vcc
	s_nop 0
	v_cmp_le_u32 vcc, v38, v20
	v_addc_co_u32 v40, vcc, 0, v40, vcc
	s_nop 0
	v_cmp_le_u32 vcc, v38, v26
	v_addc_co_u32 v40, vcc, 0, v40, vcc
	s_nop 0
	v_cmp_le_u32 vcc, v38, v24
	v_addc_co_u32 v40, vcc, 0, v40, vcc
	s_nop 0
	v_cmp_le_u32 vcc, v38, v30
	v_addc_co_u32 v40, vcc, 0, v40, vcc
	s_nop 0
	v_cmp_le_u32 vcc, v38, v28
	v_addc_co_u32 v40, vcc, 0, v40, vcc
	s_nop 0
	v_cmp_le_u32 vcc, v38, v83
	v_addc_co_u32 v40, vcc, 0, v40, vcc
	s_nop 0
	v_cmp_le_u32 vcc, v38, v81
	v_addc_co_u32 v40, vcc, 0, v40, vcc
	s_nop 0
	v_cmp_le_u32 vcc, v38, v87
	v_addc_co_u32 v40, vcc, 0, v40, vcc
	s_nop 0
	v_cmp_le_u32 vcc, v38, v85
	v_addc_co_u32 v40, vcc, 0, v40, vcc
	s_nop 0
	v_cmp_le_u32 vcc, v38, v91
	v_addc_co_u32 v40, vcc, 0, v40, vcc
	s_nop 0
	v_cmp_le_u32 vcc, v38, v89
	v_addc_co_u32 v40, vcc, 0, v40, vcc
	s_nop 0
	v_cmp_le_u32 vcc, v38, v95
	v_addc_co_u32 v40, vcc, 0, v40, vcc
	s_nop 0
	v_cmp_le_u32 vcc, v38, v93
	v_addc_co_u32 v40, vcc, 0, v40, vcc
	s_nop 0
	v_cmp_le_u32 vcc, v38, v99
	v_addc_co_u32 v40, vcc, 0, v40, vcc
	s_nop 0
	v_cmp_le_u32 vcc, v38, v97
	v_addc_co_u32 v40, vcc, 0, v40, vcc
	s_nop 0
	v_cmp_le_u32 vcc, v38, v32
	v_addc_co_u32 v40, vcc, 0, v40, vcc
	s_nop 0
	v_cmp_le_u32 vcc, v38, v101
	v_addc_co_u32 v40, vcc, 0, v40, vcc
	s_nop 0
	v_cmp_le_u32 vcc, v38, v105
	v_addc_co_u32 v40, vcc, 0, v40, vcc
	s_nop 0
	v_cmp_le_u32 vcc, v38, v103
	v_addc_co_u32 v40, vcc, 0, v40, vcc
	s_nop 0
	v_cmp_le_u32 vcc, v38, v109
	v_addc_co_u32 v40, vcc, 0, v40, vcc
	s_nop 0
	v_cmp_le_u32 vcc, v38, v107
	v_addc_co_u32 v40, vcc, 0, v40, vcc
	s_nop 0
	v_cmp_le_u32 vcc, v38, v113
	v_addc_co_u32 v40, vcc, 0, v40, vcc
	s_nop 0
	v_cmp_le_u32 vcc, v38, v111
	v_addc_co_u32 v40, vcc, 0, v40, vcc
	s_nop 1
	v_add_u32_dpp v40, v40, v40 row_shr:1 row_mask:0xf bank_mask:0xf bound_ctrl:0
	s_nop 1
	v_add_u32_dpp v40, v40, v40 row_shr:2 row_mask:0xf bank_mask:0xf bound_ctrl:0
	s_nop 1
	v_add_u32_dpp v40, v40, v40 row_shr:4 row_mask:0xf bank_mask:0xf bound_ctrl:0
	s_nop 1
	v_add_u32_dpp v40, v40, v40 row_shr:8 row_mask:0xf bank_mask:0xf bound_ctrl:0
	s_nop 1
	v_add_u32_dpp v40, v40, v40 row_bcast:15 row_mask:0xa bank_mask:0xf
	s_nop 1
	v_add_u32_dpp v40, v40, v40 row_bcast:31 row_mask:0xc bank_mask:0xf
	s_nop 1
	v_readlane_b32 s98, v40, 63
	s_nop 1
	v_mov_b32_e32 v40, s98
	v_cmp_lt_i32_e32 vcc, s38, v40
	s_nop 1
	v_cndmask_b32_e32 v115, v0, v38, vcc
	v_cmp_lt_i32_e32 vcc, s39, v40
	s_nop 1
	v_cndmask_b32_e32 v36, v38, v36, vcc
	v_cmp_eq_u32_e32 vcc, s38, v40
	s_nop 1
	v_cndmask_b32_e32 v0, v115, v0, vcc
	v_cndmask_b32_e32 v34, v34, v38, vcc
	v_sub_u32_e32 v38, v36, v0
	v_cmp_gt_u32_e64 s[6:7], 2, v38
	s_or_b64 s[6:7], vcc, s[6:7]
	s_and_b64 s[6:7], exec, s[6:7]
	s_or_b64 s[24:25], s[6:7], s[24:25]
	s_andn2_b64 s[6:7], s[26:27], exec
	s_and_b64 s[26:27], vcc, exec
	s_or_b64 s[26:27], s[6:7], s[26:27]
	s_andn2_b64 exec, exec, s[24:25]
	s_cbranch_execnz .LBB0_806
	s_or_b64 exec, exec, s[24:25]
	s_andn2_b64 s[6:7], s[20:21], exec
	s_and_b64 s[20:21], s[26:27], exec
	s_or_b64 s[20:21], s[6:7], s[20:21]

; template <int NJ>
; DI void select_row(const float* row, int n, u64* bmrow, int lane) {
;     ...
;         const unsigned cand = X | (1u << bit);
;         int c = 0;
; #pragma unroll
;         for (int jj = 0; jj < NJ; ++jj) {
;           unsigned tmp;
;           asm volatile("v_add_u32 %1, %7, %5\n\tv_cmp_eq_u32 vcc, %2, %3\n\tv_cndmask_b32 %1, %4, %1, vcc\n\tv_cmp_gt_u32 vcc, %6, %1\n\tv_addc_co_u32 %0, vcc, 0, %0, vcc"
;                        : "+v"(c), "=&v"(tmp) : "s"(T), "v"(key[jj]), "v"(bigv), "v"(lane), "s"(cand), "n"(jj * 64) : "vcc");
;         }
;         c = wave_sum_i(c, lane);
;         if (c <= need) X = cand;
;       }
.LBB0_811:
	v_mov_b32_e32 v115, v1
	v_lshl_or_b32 v40, 1, s22, v36
	v_add_u32 v117, 0, v2
	v_cmp_eq_u32 vcc, v0, v79
	v_cndmask_b32 v117, v38, v117, vcc
	v_cmp_gt_u32 vcc, v40, v117
	v_addc_co_u32 v115, vcc, 0, v115, vcc
	s_add_i32 s22, s22, -1
	v_add_u32 v117, 64, v2
	v_cmp_eq_u32 vcc, v0, v77
	v_cndmask_b32 v117, v38, v117, vcc
	v_cmp_gt_u32 vcc, v40, v117
	v_addc_co_u32 v115, vcc, 0, v115, vcc
	s_cmp_lg_u32 s22, -1
	v_add_u32 v117, 0x80, v2
	v_cmp_eq_u32 vcc, v0, v75
	v_cndmask_b32 v117, v38, v117, vcc
	v_cmp_gt_u32 vcc, v40, v117
	v_addc_co_u32 v115, vcc, 0, v115, vcc
	s_nop 0
	v_add_u32 v117, 0xc0, v2
	v_cmp_eq_u32 vcc, v0, v73
	v_cndmask_b32 v117, v38, v117, vcc
	v_cmp_gt_u32 vcc, v40, v117
	v_addc_co_u32 v115, vcc, 0, v115, vcc
	s_nop 0
	v_add_u32 v117, 0x100, v2
	v_cmp_eq_u32 vcc, v0, v71
	v_cndmask_b32 v117, v38, v117, vcc
	v_cmp_gt_u32 vcc, v40, v117
	v_addc_co_u32 v115, vcc, 0, v115, vcc
	s_nop 0
	v_add_u32 v117, 0x140, v2
	v_cmp_eq_u32 vcc, v0, v69
	v_cndmask_b32 v117, v38, v117, vcc
	v_cmp_gt_u32 vcc, v40, v117
	v_addc_co_u32 v115, vcc, 0, v115, vcc
	s_nop 0
	v_add_u32 v117, 0x180, v2
	v_cmp_eq_u32 vcc, v0, v67
	v_cndmask_b32 v117, v38, v117, vcc
	v_cmp_gt_u32 vcc, v40, v117
	v_addc_co_u32 v115, vcc, 0, v115, vcc
	s_nop 0
	v_add_u32 v117, 0x1c0, v2
	v_cmp_eq_u32 vcc, v0, v65
	v_cndmask_b32 v117, v38, v117, vcc
	v_cmp_gt_u32 vcc, v40, v117
	v_addc_co_u32 v115, vcc, 0, v115, vcc
	s_nop 0
	v_add_u32 v117, 0x200, v2
	v_cmp_eq_u32 vcc, v0, v63
	v_cndmask_b32 v117, v38, v117, vcc
	v_cmp_gt_u32 vcc, v40, v117
	v_addc_co_u32 v115, vcc, 0, v115, vcc
	s_nop 0
	v_add_u32 v117, 0x240, v2
	v_cmp_eq_u32 vcc, v0, v61
	v_cndmask_b32 v117, v38, v117, vcc
	v_cmp_gt_u32 vcc, v40, v117
	v_addc_co_u32 v115, vcc, 0, v115, vcc
	s_nop 0
	v_add_u32 v117, 0x280, v2
	v_cmp_eq_u32 vcc, v0, v59
	v_cndmask_b32 v117, v38, v117, vcc
	v_cmp_gt_u32 vcc, v40, v117
	v_addc_co_u32 v115, vcc, 0, v115, vcc
	s_nop 0
	v_add_u32 v117, 0x2c0, v2
	v_cmp_eq_u32 vcc, v0, v57
	v_cndmask_b32 v117, v38, v117, vcc
	v_cmp_gt_u32 vcc, v40, v117
	v_addc_co_u32 v115, vcc, 0, v115, vcc
	s_nop 0
	v_add_u32 v117, 0x300, v2
	v_cmp_eq_u32 vcc, v0, v55
	v_cndmask_b32 v117, v38, v117, vcc
	v_cmp_gt_u32 vcc, v40, v117
	v_addc_co_u32 v115, vcc, 0, v115, vcc
	s_nop 0
	v_add_u32 v117, 0x340, v2
	v_cmp_eq_u32 vcc, v0, v51
	v_cndmask_b32 v117, v38, v117, vcc
	v_cmp_gt_u32 vcc, v40, v117
	v_addc_co_u32 v115, vcc, 0, v115, vcc
	s_nop 0
	v_add_u32 v117, 0x380, v2
	v_cmp_eq_u32 vcc, v0, v53
	v_cndmask_b32 v117, v38, v117, vcc
	v_cmp_gt_u32 vcc, v40, v117
	v_addc_co_u32 v115, vcc, 0, v115, vcc
	s_nop 0
	v_add_u32 v117, 0x3c0, v2
	v_cmp_eq_u32 vcc, v0, v49
	v_cndmask_b32 v117, v38, v117, vcc
	v_cmp_gt_u32 vcc, v40, v117
	v_addc_co_u32 v115, vcc, 0, v115, vcc
	s_nop 0
	v_add_u32 v117, 0x400, v2
	v_cmp_eq_u32 vcc, v0, v47
	v_cndmask_b32 v117, v38, v117, vcc
	v_cmp_gt_u32 vcc, v40, v117
	v_addc_co_u32 v115, vcc, 0, v115, vcc
	s_nop 0
	v_add_u32 v117, 0x440, v2
	v_cmp_eq_u32 vcc, v0, v45
	v_cndmask_b32 v117, v38, v117, vcc
	v_cmp_gt_u32 vcc, v40, v117
	v_addc_co_u32 v115, vcc, 0, v115, vcc
	s_nop 0
	v_add_u32 v117, 0x480, v2
	v_cmp_eq_u32 vcc, v0, v43
	v_cndmask_b32 v117, v38, v117, vcc
	v_cmp_gt_u32 vcc, v40, v117
	v_addc_co_u32 v115, vcc, 0, v115, vcc
	s_nop 0
	v_add_u32 v117, 0x4c0, v2
	v_cmp_eq_u32 vcc, v0, v41
	v_cndmask_b32 v117, v38, v117, vcc
	v_cmp_gt_u32 vcc, v40, v117
	v_addc_co_u32 v115, vcc, 0, v115, vcc
	s_nop 0
	v_add_u32 v117, 0x500, v2
	v_cmp_eq_u32 vcc, v0, v39
	v_cndmask_b32 v117, v38, v117, vcc
	v_cmp_gt_u32 vcc, v40, v117
	v_addc_co_u32 v115, vcc, 0, v115, vcc
	s_nop 0
	v_add_u32 v117, 0x540, v2
	v_cmp_eq_u32 vcc, v0, v37
	v_cndmask_b32 v117, v38, v117, vcc
	v_cmp_gt_u32 vcc, v40, v117
	v_addc_co_u32 v115, vcc, 0, v115, vcc
	s_nop 0
	v_add_u32 v117, 0x580, v2
	v_cmp_eq_u32 vcc, v0, v35
	v_cndmask_b32 v117, v38, v117, vcc
	v_cmp_gt_u32 vcc, v40, v117
	v_addc_co_u32 v115, vcc, 0, v115, vcc
	s_nop 0
	v_add_u32 v117, 0x5c0, v2
	v_cmp_eq_u32 vcc, v0, v33
	v_cndmask_b32 v117, v38, v117, vcc
	v_cmp_gt_u32 vcc, v40, v117
	v_addc_co_u32 v115, vcc, 0, v115, vcc
	s_nop 0
	v_add_u32 v117, 0x600, v2
	v_cmp_eq_u32 vcc, v0, v31
	v_cndmask_b32 v117, v38, v117, vcc
	v_cmp_gt_u32 vcc, v40, v117
	v_addc_co_u32 v115, vcc, 0, v115, vcc
	s_nop 0
	v_add_u32 v117, 0x640, v2
	v_cmp_eq_u32 vcc, v0, v29
	v_cndmask_b32 v117, v38, v117, vcc
	v_cmp_gt_u32 vcc, v40, v117
	v_addc_co_u32 v115, vcc, 0, v115, vcc
	s_nop 0
	v_add_u32 v117, 0x680, v2
	v_cmp_eq_u32 vcc, v0, v27
	v_cndmask_b32 v117, v38, v117, vcc
	v_cmp_gt_u32 vcc, v40, v117
	v_addc_co_u32 v115, vcc, 0, v115, vcc
	s_nop 0
	v_add_u32 v117, 0x6c0, v2
	v_cmp_eq_u32 vcc, v0, v25
	v_cndmask_b32 v117, v38, v117, vcc
	v_cmp_gt_u32 vcc, v40, v117
	v_addc_co_u32 v115, vcc, 0, v115, vcc
	s_nop 0
	v_add_u32 v117, 0x700, v2
	v_cmp_eq_u32 vcc, v0, v23
	v_cndmask_b32 v117, v38, v117, vcc
	v_cmp_gt_u32 vcc, v40, v117
	v_addc_co_u32 v115, vcc, 0, v115, vcc
	s_nop 0
	v_add_u32 v117, 0x740, v2
	v_cmp_eq_u32 vcc, v0, v21
	v_cndmask_b32 v117, v38, v117, vcc
	v_cmp_gt_u32 vcc, v40, v117
	v_addc_co_u32 v115, vcc, 0, v115, vcc
	s_nop 0
	v_add_u32 v117, 0x780, v2
	v_cmp_eq_u32 vcc, v0, v19
	v_cndmask_b32 v117, v38, v117, vcc
	v_cmp_gt_u32 vcc, v40, v117
	v_addc_co_u32 v115, vcc, 0, v115, vcc
	s_nop 0
	v_add_u32 v117, 0x7c0, v2
	v_cmp_eq_u32 vcc, v0, v17
	v_cndmask_b32 v117, v38, v117, vcc
	v_cmp_gt_u32 vcc, v40, v117
	v_addc_co_u32 v115, vcc, 0, v115, vcc
	s_nop 0
	v_add_u32 v117, 0x800, v2
	v_cmp_eq_u32 vcc, v0, v6
	v_cndmask_b32 v117, v38, v117, vcc
	v_cmp_gt_u32 vcc, v40, v117
	v_addc_co_u32 v115, vcc, 0, v115, vcc
	s_nop 0
	v_add_u32 v117, 0x840, v2
	v_cmp_eq_u32 vcc, v0, v4
; DI int shflxi(int v, int m, int lane) { return __builtin_amdgcn_ds_bpermute((lane ^ m) << 2, v); }
; DI int wave_sum_i(int v, int lane) {
; #pragma unroll
;   for (int o = 32; o > 0; o >>= 1) v += shflxi(v, o, lane);
;   return v;
; }
; template <int NJ>
; DI void select_row(const float* row, int n, u64* bmrow, int lane) {
;     ...
;         const unsigned cand = X | (1u << bit);
;         int c = 0;
; #pragma unroll
;         for (int jj = 0; jj < NJ; ++jj) {
;           unsigned tmp;
;           asm volatile("v_add_u32 %1, %7, %5\n\tv_cmp_eq_u32 vcc, %2, %3\n\tv_cndmask_b32 %1, %4, %1, vcc\n\tv_cmp_gt_u32 vcc, %6, %1\n\tv_addc_co_u32 %0, vcc, 0, %0, vcc"
;                        : "+v"(c), "=&v"(tmp) : "s"(T), "v"(key[jj]), "v"(bigv), "v"(lane), "s"(cand), "n"(jj * 64) : "vcc");
;         }
;         c = wave_sum_i(c, lane);
;         if (c <= need) X = cand;
;       }
	v_cndmask_b32 v117, v38, v117, vcc
	v_cmp_gt_u32 vcc, v40, v117
	v_addc_co_u32 v115, vcc, 0, v115, vcc
	s_nop 0
	v_add_u32 v117, 0x880, v2
	v_cmp_eq_u32 vcc, v0, v10
	v_cndmask_b32 v117, v38, v117, vcc
	v_cmp_gt_u32 vcc, v40, v117
	v_addc_co_u32 v115, vcc, 0, v115, vcc
	s_nop 0
	v_add_u32 v117, 0x8c0, v2
	v_cmp_eq_u32 vcc, v0, v8
	v_cndmask_b32 v117, v38, v117, vcc
	v_cmp_gt_u32 vcc, v40, v117
	v_addc_co_u32 v115, vcc, 0, v115, vcc
	s_nop 0
	v_add_u32 v117, 0x900, v2
	v_cmp_eq_u32 vcc, v0, v14
	v_cndmask_b32 v117, v38, v117, vcc
	v_cmp_gt_u32 vcc, v40, v117
	v_addc_co_u32 v115, vcc, 0, v115, vcc
	s_nop 0
	v_add_u32 v117, 0x940, v2
	v_cmp_eq_u32 vcc, v0, v12
	v_cndmask_b32 v117, v38, v117, vcc
	v_cmp_gt_u32 vcc, v40, v117
	v_addc_co_u32 v115, vcc, 0, v115, vcc
	s_nop 0
	v_add_u32 v117, 0x980, v2
	v_cmp_eq_u32 vcc, v0, v18
	v_cndmask_b32 v117, v38, v117, vcc
	v_cmp_gt_u32 vcc, v40, v117
	v_addc_co_u32 v115, vcc, 0, v115, vcc
	s_nop 0
	v_add_u32 v117, 0x9c0, v2
	v_cmp_eq_u32 vcc, v0, v16
	v_cndmask_b32 v117, v38, v117, vcc
	v_cmp_gt_u32 vcc, v40, v117
	v_addc_co_u32 v115, vcc, 0, v115, vcc
	s_nop 0
	v_add_u32 v117, 0xa00, v2
	v_cmp_eq_u32 vcc, v0, v22
	v_cndmask_b32 v117, v38, v117, vcc
	v_cmp_gt_u32 vcc, v40, v117
	v_addc_co_u32 v115, vcc, 0, v115, vcc
	s_nop 0
	v_add_u32 v117, 0xa40, v2
	v_cmp_eq_u32 vcc, v0, v20
	v_cndmask_b32 v117, v38, v117, vcc
	v_cmp_gt_u32 vcc, v40, v117
	v_addc_co_u32 v115, vcc, 0, v115, vcc
	s_nop 0
	v_add_u32 v117, 0xa80, v2
	v_cmp_eq_u32 vcc, v0, v26
	v_cndmask_b32 v117, v38, v117, vcc
	v_cmp_gt_u32 vcc, v40, v117
	v_addc_co_u32 v115, vcc, 0, v115, vcc
	s_nop 0
	v_add_u32 v117, 0xac0, v2
	v_cmp_eq_u32 vcc, v0, v24
	v_cndmask_b32 v117, v38, v117, vcc
	v_cmp_gt_u32 vcc, v40, v117
	v_addc_co_u32 v115, vcc, 0, v115, vcc
	s_nop 0
	v_add_u32 v117, 0xb00, v2
	v_cmp_eq_u32 vcc, v0, v30
	v_cndmask_b32 v117, v38, v117, vcc
	v_cmp_gt_u32 vcc, v40, v117
	v_addc_co_u32 v115, vcc, 0, v115, vcc
	s_nop 0
	v_add_u32 v117, 0xb40, v2
	v_cmp_eq_u32 vcc, v0, v28
	v_cndmask_b32 v117, v38, v117, vcc
	v_cmp_gt_u32 vcc, v40, v117
	v_addc_co_u32 v115, vcc, 0, v115, vcc
	s_nop 0
	v_add_u32 v117, 0xb80, v2
	v_cmp_eq_u32 vcc, v0, v83
	v_cndmask_b32 v117, v38, v117, vcc
	v_cmp_gt_u32 vcc, v40, v117
	v_addc_co_u32 v115, vcc, 0, v115, vcc
	s_nop 0
	v_add_u32 v117, 0xbc0, v2
	v_cmp_eq_u32 vcc, v0, v81
	v_cndmask_b32 v117, v38, v117, vcc
	v_cmp_gt_u32 vcc, v40, v117
	v_addc_co_u32 v115, vcc, 0, v115, vcc
	s_nop 0
	v_add_u32 v117, 0xc00, v2
	v_cmp_eq_u32 vcc, v0, v87
	v_cndmask_b32 v117, v38, v117, vcc
	v_cmp_gt_u32 vcc, v40, v117
	v_addc_co_u32 v115, vcc, 0, v115, vcc
	s_nop 0
	v_add_u32 v117, 0xc40, v2
	v_cmp_eq_u32 vcc, v0, v85
	v_cndmask_b32 v117, v38, v117, vcc
	v_cmp_gt_u32 vcc, v40, v117
	v_addc_co_u32 v115, vcc, 0, v115, vcc
	s_nop 0
	v_add_u32 v117, 0xc80, v2
	v_cmp_eq_u32 vcc, v0, v91
	v_cndmask_b32 v117, v38, v117, vcc
	v_cmp_gt_u32 vcc, v40, v117
	v_addc_co_u32 v115, vcc, 0, v115, vcc
	s_nop 0
	v_add_u32 v117, 0xcc0, v2
	v_cmp_eq_u32 vcc, v0, v89
	v_cndmask_b32 v117, v38, v117, vcc
	v_cmp_gt_u32 vcc, v40, v117
	v_addc_co_u32 v115, vcc, 0, v115, vcc
	s_nop 0
	v_add_u32 v117, 0xd00, v2
	v_cmp_eq_u32 vcc, v0, v95
	v_cndmask_b32 v117, v38, v117, vcc
	v_cmp_gt_u32 vcc, v40, v117
	v_addc_co_u32 v115, vcc, 0, v115, vcc
	s_nop 0
	v_add_u32 v117, 0xd40, v2
	v_cmp_eq_u32 vcc, v0, v93
	v_cndmask_b32 v117, v38, v117, vcc
	v_cmp_gt_u32 vcc, v40, v117
	v_addc_co_u32 v115, vcc, 0, v115, vcc
	s_nop 0
	v_add_u32 v117, 0xd80, v2
	v_cmp_eq_u32 vcc, v0, v99
	v_cndmask_b32 v117, v38, v117, vcc
	v_cmp_gt_u32 vcc, v40, v117
	v_addc_co_u32 v115, vcc, 0, v115, vcc
	s_nop 0
	v_add_u32 v117, 0xdc0, v2
	v_cmp_eq_u32 vcc, v0, v97
	v_cndmask_b32 v117, v38, v117, vcc
	v_cmp_gt_u32 vcc, v40, v117
	v_addc_co_u32 v115, vcc, 0, v115, vcc
	s_nop 0
	v_add_u32 v117, 0xe00, v2
	v_cmp_eq_u32 vcc, v0, v32
	v_cndmask_b32 v117, v38, v117, vcc
	v_cmp_gt_u32 vcc, v40, v117
	v_addc_co_u32 v115, vcc, 0, v115, vcc
	s_nop 0
	v_add_u32 v117, 0xe40, v2
	v_cmp_eq_u32 vcc, v0, v101
	v_cndmask_b32 v117, v38, v117, vcc
	v_cmp_gt_u32 vcc, v40, v117
	v_addc_co_u32 v115, vcc, 0, v115, vcc
	s_nop 0
	v_add_u32 v117, 0xe80, v2
	v_cmp_eq_u32 vcc, v0, v105
	v_cndmask_b32 v117, v38, v117, vcc
	v_cmp_gt_u32 vcc, v40, v117
	v_addc_co_u32 v115, vcc, 0, v115, vcc
	s_nop 0
	v_add_u32 v117, 0xec0, v2
	v_cmp_eq_u32 vcc, v0, v103
	v_cndmask_b32 v117, v38, v117, vcc
	v_cmp_gt_u32 vcc, v40, v117
	v_addc_co_u32 v115, vcc, 0, v115, vcc
	s_nop 0
	v_add_u32 v117, 0xf00, v2
	v_cmp_eq_u32 vcc, v0, v109
	v_cndmask_b32 v117, v38, v117, vcc
	v_cmp_gt_u32 vcc, v40, v117
	v_addc_co_u32 v115, vcc, 0, v115, vcc
	s_nop 0
	v_add_u32 v117, 0xf40, v2
	v_cmp_eq_u32 vcc, v0, v107
	v_cndmask_b32 v117, v38, v117, vcc
	v_cmp_gt_u32 vcc, v40, v117
	v_addc_co_u32 v115, vcc, 0, v115, vcc
	s_nop 0
	v_add_u32 v117, 0xf80, v2
	v_cmp_eq_u32 vcc, v0, v113
	v_cndmask_b32 v117, v38, v117, vcc
	v_cmp_gt_u32 vcc, v40, v117
	v_addc_co_u32 v115, vcc, 0, v115, vcc
	s_nop 0
	v_add_u32 v117, 0xfc0, v2
	v_cmp_eq_u32 vcc, v0, v111
	v_cndmask_b32 v117, v38, v117, vcc
	v_cmp_gt_u32 vcc, v40, v117
	v_addc_co_u32 v115, vcc, 0, v115, vcc
	s_nop 1
	v_add_u32_dpp v115, v115, v115 row_shr:1 row_mask:0xf bank_mask:0xf bound_ctrl:0
	s_nop 1
	v_add_u32_dpp v115, v115, v115 row_shr:2 row_mask:0xf bank_mask:0xf bound_ctrl:0
	s_nop 1
	v_add_u32_dpp v115, v115, v115 row_shr:4 row_mask:0xf bank_mask:0xf bound_ctrl:0
	s_nop 1
	v_add_u32_dpp v115, v115, v115 row_shr:8 row_mask:0xf bank_mask:0xf bound_ctrl:0
	s_nop 1
	v_add_u32_dpp v115, v115, v115 row_bcast:15 row_mask:0xa bank_mask:0xf
	s_nop 1
	v_add_u32_dpp v115, v115, v115 row_bcast:31 row_mask:0xc bank_mask:0xf
	s_nop 1
	v_readlane_b32 s98, v115, 63
	s_nop 1
	v_mov_b32_e32 v115, s98
	v_cmp_gt_i32_e32 vcc, v115, v34
	s_nop 1
	v_cndmask_b32_e32 v36, v40, v36, vcc
	s_cbranch_scc1 .LBB0_811
